# GEMM K-loops: no priority flip between the two MFMA blocks of a segment, and the closing barrier is signalled before the priority is lowered
# baseline (speedup 1.0000x reference)
; #define PG8_STAGE(bufoff, gbase, voff) do { _Pragma("unroll") for (int _i = 0; _i < 2; ++_i) \
;         __builtin_amdgcn_global_load_lds((const unsigned*)((const char*)(gbase) + (voff)[_i]), (PG8_LAS unsigned*)(lds + (bufoff) + ldsw + _i * 8192), 16, 0, 0); } while (0)
; #define PG8_LDA(dst, b, h) do { _Pragma("unroll") for (int m = 0; m < 4; ++m) _Pragma("unroll") for (int k = 0; k < 2; ++k) dst[m][k] = *(const PG8_LAS bf16x8*)(lds + PG8_SA(b, h) + aoff + m * 2048 + k * 1024); } while (0)
; #define PG8_LDB(dst, b, h) do { _Pragma("unroll") for (int n = 0; n < 2; ++n) _Pragma("unroll") for (int k = 0; k < 2; ++k) dst[n][k] = *(const PG8_LAS bf16x8*)(lds + PG8_SB(b, h) + boff + n * 2048 + k * 1024); } while (0)
; #define PG8_WAIT_V(n) asm volatile("s_waitcnt vmcnt(" #n ")" ::: "memory")
; #define PG8_WAIT_L(n) asm volatile("s_waitcnt lgkmcnt(" #n ")" ::: "memory")
; #define PG8_BAR __builtin_amdgcn_s_barrier()
; #define PG8_SCHED __builtin_amdgcn_sched_barrier(0)
; template <class Epi, class Sched, bool ALIGN_EPI = false, bool SP2 = false>
; __device__ __forceinline__ void gemm_phase(PG8_LAS unsigned char* lds, const Gemm g, const Sched& S, const Epi& E) {
;     ...
;         const char* nA = has_next ? (const char*)g.A + S.a_byte(nxt, K) : cA; const char* nB = has_next ? (const char*)g.Bt + (size_t)nxt.pn * tstep : cB;
;         for (int t = 0; t < nt; t += 2) {
;             const bool last = (t == nt - 2);
;             const char* a1 = cA + (size_t)(t + 1) * kstep;
;             const char* a2 = last ? nA : cA + (size_t)(t + 2) * kstep; const char* b2 = last ? nB : cB + (size_t)(t + 2) * kstep;
;             const char* a3 = a2 + kstep; const char* b3 = b2 + kstep;
;             if (last && has_next) S.a_ready(nxt);
;             if constexpr (SP2) {
;             PG8_LDB(B0, 0, 0); PG8_LDB(B1, 0, 1); PG8_SCHED; PG8_LDA(At, 0, 0); PG8_STAGE(PG8_SA(1, 1), a1 + hstep, voffA);
;             PG8_WAIT_V(8); PG8_WAIT_L(0); PG8_BAR; PG8_MMA(0, 0, At, B0); PG8_MMA(0, 1, At, B1); PG8_BAR; PG8_SCHED;
;             PG8_LDA(At, 0, 1); PG8_STAGE(PG8_SB(0, 0), b2, voffB); PG8_STAGE(PG8_SB(0, 1), b2 + hstep, voffB); PG8_STAGE(PG8_SA(0, 0), a2, voffA);
;             PG8_WAIT_V(8); PG8_WAIT_L(0); PG8_BAR; PG8_MMA(1, 0, At, B0); PG8_MMA(1, 1, At, B1); PG8_BAR; PG8_SCHED;
.LBB0_62:
	s_add_i32 s79, s58, 2
	s_add_u32 s18, s56, 0x80
	s_addc_u32 s19, s57, 0
	s_add_i32 s86, 0, 0x10000
	s_cmp_eq_u32 s72, s58
	s_cselect_b32 s59, s9, s19
	s_cselect_b32 s58, s8, s18
	s_cselect_b32 s85, s55, s78
	s_cselect_b32 s84, s54, s38
	s_add_i32 s18, 0, 0x14000
	v_add_u32_e32 v76, s86, v248
	v_add_u32_e32 v156, s18, v248
	ds_read_b128 v[64:67], v76
	ds_read_b128 v[68:71], v76 offset:1024
	ds_read_b128 v[72:75], v76 offset:2048
	ds_read_b128 v[76:79], v76 offset:3072
	ds_read_b128 v[144:147], v156
	ds_read_b128 v[148:151], v156 offset:1024
	ds_read_b128 v[152:155], v156 offset:2048
	ds_read_b128 v[156:159], v156 offset:3072
	v_lshl_add_u64 v[192:193], s[56:57], 0, v[224:225]
	s_add_i32 m0, s64, 0xc000
	ds_read_b128 v[160:163], v250
	ds_read_b128 v[164:167], v250 offset:1024
	ds_read_b128 v[168:171], v250 offset:2048
	ds_read_b128 v[172:175], v250 offset:3072
	ds_read_b128 v[176:179], v250 offset:4096
	ds_read_b128 v[180:183], v250 offset:5120
	ds_read_b128 v[184:187], v250 offset:6144
	ds_read_b128 v[188:191], v250 offset:7168
	global_load_lds_dwordx4 v[192:193], off
	v_lshl_add_u64 v[192:193], s[56:57], 0, v[226:227]
	s_add_i32 m0, s64, 0xe000
	s_nop 0
	global_load_lds_dwordx4 v[192:193], off
	s_waitcnt vmcnt(8)
	s_waitcnt lgkmcnt(0)
	s_setprio 1
	s_barrier
	v_mfma_f32_16x16x32_bf16 v[140:143], v[64:67], v[160:163], v[140:143]
	v_mfma_f32_16x16x32_bf16 v[136:139], v[72:75], v[160:163], v[136:139]
	v_mfma_f32_16x16x32_bf16 v[124:127], v[64:67], v[168:171], v[124:127]
	v_mfma_f32_16x16x32_bf16 v[120:123], v[72:75], v[168:171], v[120:123]
	v_mfma_f32_16x16x32_bf16 v[108:111], v[64:67], v[176:179], v[108:111]
	v_mfma_f32_16x16x32_bf16 v[104:107], v[72:75], v[176:179], v[104:107]
	v_mfma_f32_16x16x32_bf16 v[92:95], v[64:67], v[184:187], v[92:95]
	v_mfma_f32_16x16x32_bf16 v[88:91], v[72:75], v[184:187], v[88:91]
	v_mfma_f32_16x16x32_bf16 v[140:143], v[68:71], v[164:167], v[140:143]
	v_mfma_f32_16x16x32_bf16 v[136:139], v[76:79], v[164:167], v[136:139]
	v_mfma_f32_16x16x32_bf16 v[124:127], v[68:71], v[172:175], v[124:127]
	v_mfma_f32_16x16x32_bf16 v[120:123], v[76:79], v[172:175], v[120:123]
	v_mfma_f32_16x16x32_bf16 v[108:111], v[68:71], v[180:183], v[108:111]
	v_mfma_f32_16x16x32_bf16 v[104:107], v[76:79], v[180:183], v[104:107]
	v_mfma_f32_16x16x32_bf16 v[92:95], v[68:71], v[188:191], v[92:95]
	v_mfma_f32_16x16x32_bf16 v[88:91], v[76:79], v[188:191], v[88:91]
	v_mfma_f32_16x16x32_bf16 v[132:135], v[144:147], v[160:163], v[132:135]
	v_mfma_f32_16x16x32_bf16 v[128:131], v[152:155], v[160:163], v[128:131]
	v_mfma_f32_16x16x32_bf16 v[116:119], v[144:147], v[168:171], v[116:119]
	v_mfma_f32_16x16x32_bf16 v[112:115], v[152:155], v[168:171], v[112:115]
	v_mfma_f32_16x16x32_bf16 v[100:103], v[144:147], v[176:179], v[100:103]
	v_mfma_f32_16x16x32_bf16 v[96:99], v[152:155], v[176:179], v[96:99]
	v_mfma_f32_16x16x32_bf16 v[84:87], v[144:147], v[184:187], v[84:87]
	v_mfma_f32_16x16x32_bf16 v[80:83], v[152:155], v[184:187], v[80:83]
	v_mfma_f32_16x16x32_bf16 v[132:135], v[148:151], v[164:167], v[132:135]
	v_mfma_f32_16x16x32_bf16 v[128:131], v[156:159], v[164:167], v[128:131]
	v_mfma_f32_16x16x32_bf16 v[116:119], v[148:151], v[172:175], v[116:119]
	v_mfma_f32_16x16x32_bf16 v[112:115], v[156:159], v[172:175], v[112:115]
	v_mfma_f32_16x16x32_bf16 v[100:103], v[148:151], v[180:183], v[100:103]
	v_mfma_f32_16x16x32_bf16 v[96:99], v[156:159], v[180:183], v[96:99]
	v_mfma_f32_16x16x32_bf16 v[84:87], v[148:151], v[188:191], v[84:87]
	v_mfma_f32_16x16x32_bf16 v[80:83], v[156:159], v[188:191], v[80:83]
	s_barrier
	s_setprio 0
	s_add_i32 s19, s86, s63
	v_lshl_add_u64 v[192:193], s[84:85], 0, v[208:209]
	s_mov_b32 m0, s19
	ds_read_b128 v[160:163], v250 offset:16384
	ds_read_b128 v[164:167], v250 offset:17408
	ds_read_b128 v[168:171], v250 offset:18432
	ds_read_b128 v[172:175], v250 offset:19456
	ds_read_b128 v[176:179], v250 offset:20480
	ds_read_b128 v[180:183], v250 offset:21504
	ds_read_b128 v[184:187], v250 offset:22528
	ds_read_b128 v[188:191], v250 offset:23552
	global_load_lds_dwordx4 v[192:193], off
	s_add_i32 m0, s19, 0x2000
	v_lshl_add_u64 v[194:195], s[84:85], 0, v[222:223]
	s_add_u32 s84, s84, s2
	s_addc_u32 s85, s85, 0
	s_add_i32 s18, s18, s63
	global_load_lds_dwordx4 v[194:195], off
	v_lshl_add_u64 v[196:197], s[84:85], 0, v[208:209]
	s_mov_b32 m0, s18
	v_lshl_add_u64 v[198:199], s[84:85], 0, v[222:223]
	global_load_lds_dwordx4 v[196:197], off
	s_add_i32 m0, s18, 0x2000
	v_lshl_add_u64 v[200:201], s[58:59], 0, v[218:219]
	global_load_lds_dwordx4 v[198:199], off
	s_mov_b32 m0, s64
	v_lshl_add_u64 v[202:203], s[58:59], 0, v[220:221]
	global_load_lds_dwordx4 v[200:201], off
	s_mov_b32 m0, s65
	s_nop 0
	global_load_lds_dwordx4 v[202:203], off
	s_waitcnt vmcnt(8)
	s_waitcnt lgkmcnt(0)
	s_setprio 1
	s_barrier
; #define PG8_STAGE(bufoff, gbase, voff) do { _Pragma("unroll") for (int _i = 0; _i < 2; ++_i) \
;         __builtin_amdgcn_global_load_lds((const unsigned*)((const char*)(gbase) + (voff)[_i]), (PG8_LAS unsigned*)(lds + (bufoff) + ldsw + _i * 8192), 16, 0, 0); } while (0)
; #define PG8_LDA(dst, b, h) do { _Pragma("unroll") for (int m = 0; m < 4; ++m) _Pragma("unroll") for (int k = 0; k < 2; ++k) dst[m][k] = *(const PG8_LAS bf16x8*)(lds + PG8_SA(b, h) + aoff + m * 2048 + k * 1024); } while (0)
; #define PG8_LDB(dst, b, h) do { _Pragma("unroll") for (int n = 0; n < 2; ++n) _Pragma("unroll") for (int k = 0; k < 2; ++k) dst[n][k] = *(const PG8_LAS bf16x8*)(lds + PG8_SB(b, h) + boff + n * 2048 + k * 1024); } while (0)
; #define PG8_MMA(ai, bj, At, Bt) do { __builtin_amdgcn_s_setprio(1); _Pragma("unroll") for (int m = 0; m < 4; ++m) _Pragma("unroll") for (int n = 0; n < 2; ++n) _Pragma("unroll") for (int k = 0; k < 2; ++k) \
;         acc[ai][bj][m][n] = __builtin_amdgcn_mfma_f32_16x16x32_bf16(Bt[n][k], At[m][k], acc[ai][bj][m][n], 0, 0, 0); __builtin_amdgcn_s_setprio(0); } while (0)
; #define PG8_WAIT_V(n) asm volatile("s_waitcnt vmcnt(" #n ")" ::: "memory")
; #define PG8_WAIT_L(n) asm volatile("s_waitcnt lgkmcnt(" #n ")" ::: "memory")
; #define PG8_BAR __builtin_amdgcn_s_barrier()
; #define PG8_SCHED __builtin_amdgcn_sched_barrier(0)
; template <class Epi, class Sched, bool ALIGN_EPI = false, bool SP2 = false>
; __device__ __forceinline__ void gemm_phase(PG8_LAS unsigned char* lds, const Gemm g, const Sched& S, const Epi& E) {
;     ...
;             PG8_WAIT_V(8); PG8_WAIT_L(0); PG8_BAR; PG8_MMA(1, 0, At, B0); PG8_MMA(1, 1, At, B1); PG8_BAR; PG8_SCHED;
;             PG8_LDB(B0, 1, 0); PG8_LDB(B1, 1, 1); PG8_SCHED; PG8_LDA(At, 1, 0); PG8_STAGE(PG8_SA(0, 1), a2 + hstep, voffA);
;             PG8_WAIT_V(8); PG8_WAIT_L(0); PG8_BAR; PG8_MMA(0, 0, At, B0); PG8_MMA(0, 1, At, B1); PG8_BAR; PG8_SCHED;
	v_mfma_f32_16x16x32_bf16 v[60:63], v[64:67], v[160:163], v[60:63]
	v_mfma_f32_16x16x32_bf16 v[56:59], v[72:75], v[160:163], v[56:59]
	v_mfma_f32_16x16x32_bf16 v[44:47], v[64:67], v[168:171], v[44:47]
	v_mfma_f32_16x16x32_bf16 v[40:43], v[72:75], v[168:171], v[40:43]
	v_mfma_f32_16x16x32_bf16 v[28:31], v[64:67], v[176:179], v[28:31]
	v_mfma_f32_16x16x32_bf16 v[24:27], v[72:75], v[176:179], v[24:27]
	v_mfma_f32_16x16x32_bf16 v[12:15], v[64:67], v[184:187], v[12:15]
	v_mfma_f32_16x16x32_bf16 v[8:11], v[72:75], v[184:187], v[8:11]
	v_mfma_f32_16x16x32_bf16 v[60:63], v[68:71], v[164:167], v[60:63]
	v_mfma_f32_16x16x32_bf16 v[56:59], v[76:79], v[164:167], v[56:59]
	v_mfma_f32_16x16x32_bf16 v[44:47], v[68:71], v[172:175], v[44:47]
	v_mfma_f32_16x16x32_bf16 v[40:43], v[76:79], v[172:175], v[40:43]
	v_mfma_f32_16x16x32_bf16 v[28:31], v[68:71], v[180:183], v[28:31]
	v_mfma_f32_16x16x32_bf16 v[24:27], v[76:79], v[180:183], v[24:27]
	v_mfma_f32_16x16x32_bf16 v[12:15], v[68:71], v[188:191], v[12:15]
	v_mfma_f32_16x16x32_bf16 v[8:11], v[76:79], v[188:191], v[8:11]
	v_mfma_f32_16x16x32_bf16 v[52:55], v[144:147], v[160:163], v[52:55]
	v_mfma_f32_16x16x32_bf16 v[48:51], v[152:155], v[160:163], v[48:51]
	v_mfma_f32_16x16x32_bf16 v[36:39], v[144:147], v[168:171], v[36:39]
	v_mfma_f32_16x16x32_bf16 v[32:35], v[152:155], v[168:171], v[32:35]
	v_mfma_f32_16x16x32_bf16 v[20:23], v[144:147], v[176:179], v[20:23]
	v_mfma_f32_16x16x32_bf16 v[16:19], v[152:155], v[176:179], v[16:19]
	v_mfma_f32_16x16x32_bf16 v[4:7], v[144:147], v[184:187], v[4:7]
	v_mfma_f32_16x16x32_bf16 v[0:3], v[152:155], v[184:187], v[0:3]
	v_mfma_f32_16x16x32_bf16 v[52:55], v[148:151], v[164:167], v[52:55]
	v_mfma_f32_16x16x32_bf16 v[48:51], v[156:159], v[164:167], v[48:51]
	v_mfma_f32_16x16x32_bf16 v[36:39], v[148:151], v[172:175], v[36:39]
	v_mfma_f32_16x16x32_bf16 v[32:35], v[156:159], v[172:175], v[32:35]
	v_mfma_f32_16x16x32_bf16 v[20:23], v[148:151], v[180:183], v[20:23]
	v_mfma_f32_16x16x32_bf16 v[16:19], v[156:159], v[180:183], v[16:19]
	v_mfma_f32_16x16x32_bf16 v[4:7], v[148:151], v[188:191], v[4:7]
	v_mfma_f32_16x16x32_bf16 v[0:3], v[156:159], v[188:191], v[0:3]
	s_barrier
	s_setprio 0
	s_add_i32 s18, 0, 0x18000
	s_add_i32 s19, 0, 0x1c000
	v_add_u32_e32 v76, s18, v248
	v_add_u32_e32 v156, s19, v248
	ds_read_b128 v[64:67], v76
	ds_read_b128 v[68:71], v76 offset:1024
	ds_read_b128 v[72:75], v76 offset:2048
	ds_read_b128 v[76:79], v76 offset:3072
	ds_read_b128 v[144:147], v156
	ds_read_b128 v[148:151], v156 offset:1024
	ds_read_b128 v[152:155], v156 offset:2048
	ds_read_b128 v[156:159], v156 offset:3072
	s_add_u32 s58, s58, s2
	s_addc_u32 s59, s59, 0
	s_mov_b32 m0, s66
	v_lshl_add_u64 v[204:205], s[58:59], 0, v[218:219]
	ds_read_b128 v[160:163], v250 offset:32768
	ds_read_b128 v[164:167], v250 offset:33792
	ds_read_b128 v[168:171], v250 offset:34816
	ds_read_b128 v[172:175], v250 offset:35840
	ds_read_b128 v[176:179], v250 offset:36864
	ds_read_b128 v[180:183], v250 offset:37888
	ds_read_b128 v[184:187], v250 offset:38912
	ds_read_b128 v[188:191], v250 offset:39936
	global_load_lds_dwordx4 v[204:205], off
	v_lshl_add_u64 v[204:205], s[58:59], 0, v[220:221]
	s_mov_b32 m0, s67
	s_nop 0
	global_load_lds_dwordx4 v[204:205], off
	s_waitcnt vmcnt(8)
	s_waitcnt lgkmcnt(0)
	s_setprio 1
	s_barrier
	v_mfma_f32_16x16x32_bf16 v[140:143], v[64:67], v[160:163], v[140:143]
	v_mfma_f32_16x16x32_bf16 v[136:139], v[72:75], v[160:163], v[136:139]
	v_mfma_f32_16x16x32_bf16 v[124:127], v[64:67], v[168:171], v[124:127]
	v_mfma_f32_16x16x32_bf16 v[120:123], v[72:75], v[168:171], v[120:123]
	v_mfma_f32_16x16x32_bf16 v[108:111], v[64:67], v[176:179], v[108:111]
	v_mfma_f32_16x16x32_bf16 v[104:107], v[72:75], v[176:179], v[104:107]
	v_mfma_f32_16x16x32_bf16 v[92:95], v[64:67], v[184:187], v[92:95]
	v_mfma_f32_16x16x32_bf16 v[88:91], v[72:75], v[184:187], v[88:91]
	v_mfma_f32_16x16x32_bf16 v[140:143], v[68:71], v[164:167], v[140:143]
	v_mfma_f32_16x16x32_bf16 v[136:139], v[76:79], v[164:167], v[136:139]
	v_mfma_f32_16x16x32_bf16 v[124:127], v[68:71], v[172:175], v[124:127]
	v_mfma_f32_16x16x32_bf16 v[120:123], v[76:79], v[172:175], v[120:123]
	v_mfma_f32_16x16x32_bf16 v[108:111], v[68:71], v[180:183], v[108:111]
	v_mfma_f32_16x16x32_bf16 v[104:107], v[76:79], v[180:183], v[104:107]
	v_mfma_f32_16x16x32_bf16 v[92:95], v[68:71], v[188:191], v[92:95]
	v_mfma_f32_16x16x32_bf16 v[88:91], v[76:79], v[188:191], v[88:91]
	v_mfma_f32_16x16x32_bf16 v[132:135], v[144:147], v[160:163], v[132:135]
	v_mfma_f32_16x16x32_bf16 v[128:131], v[152:155], v[160:163], v[128:131]
	v_mfma_f32_16x16x32_bf16 v[116:119], v[144:147], v[168:171], v[116:119]
	v_mfma_f32_16x16x32_bf16 v[112:115], v[152:155], v[168:171], v[112:115]
	v_mfma_f32_16x16x32_bf16 v[100:103], v[144:147], v[176:179], v[100:103]
	v_mfma_f32_16x16x32_bf16 v[96:99], v[152:155], v[176:179], v[96:99]
	v_mfma_f32_16x16x32_bf16 v[84:87], v[144:147], v[184:187], v[84:87]
	v_mfma_f32_16x16x32_bf16 v[80:83], v[152:155], v[184:187], v[80:83]
	v_mfma_f32_16x16x32_bf16 v[132:135], v[148:151], v[164:167], v[132:135]
	v_mfma_f32_16x16x32_bf16 v[128:131], v[156:159], v[164:167], v[128:131]
	v_mfma_f32_16x16x32_bf16 v[116:119], v[148:151], v[172:175], v[116:119]
	v_mfma_f32_16x16x32_bf16 v[112:115], v[156:159], v[172:175], v[112:115]
	v_mfma_f32_16x16x32_bf16 v[100:103], v[148:151], v[180:183], v[100:103]
	v_mfma_f32_16x16x32_bf16 v[96:99], v[156:159], v[180:183], v[96:99]
	v_mfma_f32_16x16x32_bf16 v[84:87], v[148:151], v[188:191], v[84:87]
	v_mfma_f32_16x16x32_bf16 v[80:83], v[156:159], v[188:191], v[80:83]
	s_barrier
; #define PG8_STAGE(bufoff, gbase, voff) do { _Pragma("unroll") for (int _i = 0; _i < 2; ++_i) \
;         __builtin_amdgcn_global_load_lds((const unsigned*)((const char*)(gbase) + (voff)[_i]), (PG8_LAS unsigned*)(lds + (bufoff) + ldsw + _i * 8192), 16, 0, 0); } while (0)
; #define PG8_LDA(dst, b, h) do { _Pragma("unroll") for (int m = 0; m < 4; ++m) _Pragma("unroll") for (int k = 0; k < 2; ++k) dst[m][k] = *(const PG8_LAS bf16x8*)(lds + PG8_SA(b, h) + aoff + m * 2048 + k * 1024); } while (0)
; #define PG8_MMA(ai, bj, At, Bt) do { __builtin_amdgcn_s_setprio(1); _Pragma("unroll") for (int m = 0; m < 4; ++m) _Pragma("unroll") for (int n = 0; n < 2; ++n) _Pragma("unroll") for (int k = 0; k < 2; ++k) \
;         acc[ai][bj][m][n] = __builtin_amdgcn_mfma_f32_16x16x32_bf16(Bt[n][k], At[m][k], acc[ai][bj][m][n], 0, 0, 0); __builtin_amdgcn_s_setprio(0); } while (0)
; #define PG8_WAIT_V(n) asm volatile("s_waitcnt vmcnt(" #n ")" ::: "memory")
; #define PG8_WAIT_L(n) asm volatile("s_waitcnt lgkmcnt(" #n ")" ::: "memory")
; #define PG8_BAR __builtin_amdgcn_s_barrier()
; #define PG8_SCHED __builtin_amdgcn_sched_barrier(0)
; template <class Epi, class Sched, bool ALIGN_EPI = false, bool SP2 = false>
; __device__ __forceinline__ void gemm_phase(PG8_LAS unsigned char* lds, const Gemm g, const Sched& S, const Epi& E) {
;     ...
;             PG8_LDA(At, 1, 1); PG8_STAGE(PG8_SB(1, 0), b3, voffB); PG8_STAGE(PG8_SB(1, 1), b3 + hstep, voffB); PG8_STAGE(PG8_SA(1, 0), a3, voffA);
;             PG8_WAIT_V(8); PG8_WAIT_L(0); PG8_BAR; PG8_MMA(1, 0, At, B0); PG8_MMA(1, 1, At, B1); PG8_BAR; PG8_SCHED;
;     ...
;         if constexpr (ALIGN_EPI) { if (wr == 0) PG8_BAR; }
	s_setprio 0
	s_add_i32 s18, s18, s63
	v_lshl_add_u64 v[192:193], v[192:193], 0, s[24:25]
	s_mov_b32 m0, s18
	ds_read_b128 v[160:163], v250 offset:49152
	ds_read_b128 v[164:167], v250 offset:50176
	ds_read_b128 v[168:171], v250 offset:51200
	ds_read_b128 v[172:175], v250 offset:52224
	ds_read_b128 v[176:179], v250 offset:53248
	ds_read_b128 v[180:183], v250 offset:54272
	ds_read_b128 v[184:187], v250 offset:55296
	ds_read_b128 v[188:191], v250 offset:56320
	global_load_lds_dwordx4 v[192:193], off
	v_lshl_add_u64 v[192:193], v[194:195], 0, s[24:25]
	s_add_i32 m0, s18, 0x2000
	s_add_i32 s18, s19, s63
	global_load_lds_dwordx4 v[192:193], off
	v_lshl_add_u64 v[192:193], v[196:197], 0, s[24:25]
	s_mov_b32 m0, s18
	s_nop 0
	global_load_lds_dwordx4 v[192:193], off
	v_lshl_add_u64 v[192:193], v[198:199], 0, s[24:25]
	s_add_i32 m0, s18, 0x2000
	s_nop 0
	global_load_lds_dwordx4 v[192:193], off
	v_lshl_add_u64 v[192:193], v[200:201], 0, s[24:25]
	s_mov_b32 m0, s68
	s_nop 0
	global_load_lds_dwordx4 v[192:193], off
	v_lshl_add_u64 v[192:193], v[202:203], 0, s[24:25]
	s_mov_b32 m0, s69
	s_nop 0
	global_load_lds_dwordx4 v[192:193], off
	s_waitcnt vmcnt(8)
	s_waitcnt lgkmcnt(0)
	s_setprio 1
	s_barrier
	v_mfma_f32_16x16x32_bf16 v[60:63], v[64:67], v[160:163], v[60:63]
	v_mfma_f32_16x16x32_bf16 v[56:59], v[72:75], v[160:163], v[56:59]
	v_mfma_f32_16x16x32_bf16 v[44:47], v[64:67], v[168:171], v[44:47]
	v_mfma_f32_16x16x32_bf16 v[40:43], v[72:75], v[168:171], v[40:43]
	v_mfma_f32_16x16x32_bf16 v[28:31], v[64:67], v[176:179], v[28:31]
	v_mfma_f32_16x16x32_bf16 v[24:27], v[72:75], v[176:179], v[24:27]
	v_mfma_f32_16x16x32_bf16 v[12:15], v[64:67], v[184:187], v[12:15]
	v_mfma_f32_16x16x32_bf16 v[8:11], v[72:75], v[184:187], v[8:11]
	v_mfma_f32_16x16x32_bf16 v[60:63], v[68:71], v[164:167], v[60:63]
	v_mfma_f32_16x16x32_bf16 v[56:59], v[76:79], v[164:167], v[56:59]
	v_mfma_f32_16x16x32_bf16 v[44:47], v[68:71], v[172:175], v[44:47]
	v_mfma_f32_16x16x32_bf16 v[40:43], v[76:79], v[172:175], v[40:43]
	v_mfma_f32_16x16x32_bf16 v[28:31], v[68:71], v[180:183], v[28:31]
	v_mfma_f32_16x16x32_bf16 v[24:27], v[76:79], v[180:183], v[24:27]
	v_mfma_f32_16x16x32_bf16 v[12:15], v[68:71], v[188:191], v[12:15]
	v_mfma_f32_16x16x32_bf16 v[8:11], v[76:79], v[188:191], v[8:11]
	v_mfma_f32_16x16x32_bf16 v[52:55], v[144:147], v[160:163], v[52:55]
	v_mfma_f32_16x16x32_bf16 v[48:51], v[152:155], v[160:163], v[48:51]
	v_mfma_f32_16x16x32_bf16 v[36:39], v[144:147], v[168:171], v[36:39]
	v_mfma_f32_16x16x32_bf16 v[32:35], v[152:155], v[168:171], v[32:35]
	v_mfma_f32_16x16x32_bf16 v[20:23], v[144:147], v[176:179], v[20:23]
	v_mfma_f32_16x16x32_bf16 v[16:19], v[152:155], v[176:179], v[16:19]
	v_mfma_f32_16x16x32_bf16 v[4:7], v[144:147], v[184:187], v[4:7]
	v_mfma_f32_16x16x32_bf16 v[0:3], v[152:155], v[184:187], v[0:3]
	v_mfma_f32_16x16x32_bf16 v[52:55], v[148:151], v[164:167], v[52:55]
	v_mfma_f32_16x16x32_bf16 v[48:51], v[156:159], v[164:167], v[48:51]
	v_mfma_f32_16x16x32_bf16 v[36:39], v[148:151], v[172:175], v[36:39]
	v_mfma_f32_16x16x32_bf16 v[32:35], v[156:159], v[172:175], v[32:35]
	v_mfma_f32_16x16x32_bf16 v[20:23], v[148:151], v[180:183], v[20:23]
	v_mfma_f32_16x16x32_bf16 v[16:19], v[156:159], v[180:183], v[16:19]
	v_mfma_f32_16x16x32_bf16 v[4:7], v[148:151], v[188:191], v[4:7]
	v_mfma_f32_16x16x32_bf16 v[0:3], v[156:159], v[188:191], v[0:3]
	s_barrier
	s_setprio 0
	s_add_u32 s56, s56, 0x100
	s_addc_u32 s57, s57, 0
	s_add_u32 s38, s38, 0x100
	s_addc_u32 s78, s78, 0
	s_cmp_ge_u32 s79, s71
	s_mov_b32 s58, s79
	s_cbranch_scc0 .LBB0_62
	s_and_b64 vcc, exec, s[48:49]
	s_cbranch_vccz .LBB0_65
	s_barrier

; #define PG8_STAGE(bufoff, gbase, voff) do { _Pragma("unroll") for (int _i = 0; _i < 2; ++_i) \
;         __builtin_amdgcn_global_load_lds((const unsigned*)((const char*)(gbase) + (voff)[_i]), (PG8_LAS unsigned*)(lds + (bufoff) + ldsw + _i * 8192), 16, 0, 0); } while (0)
; #define PG8_LDA(dst, b, h) do { _Pragma("unroll") for (int m = 0; m < 4; ++m) _Pragma("unroll") for (int k = 0; k < 2; ++k) dst[m][k] = *(const PG8_LAS bf16x8*)(lds + PG8_SA(b, h) + aoff + m * 2048 + k * 1024); } while (0)
; #define PG8_LDB(dst, b, h) do { _Pragma("unroll") for (int n = 0; n < 2; ++n) _Pragma("unroll") for (int k = 0; k < 2; ++k) dst[n][k] = *(const PG8_LAS bf16x8*)(lds + PG8_SB(b, h) + boff + n * 2048 + k * 1024); } while (0)
; #define PG8_MMA(ai, bj, At, Bt) do { __builtin_amdgcn_s_setprio(1); _Pragma("unroll") for (int m = 0; m < 4; ++m) _Pragma("unroll") for (int n = 0; n < 2; ++n) _Pragma("unroll") for (int k = 0; k < 2; ++k) \
;         acc[ai][bj][m][n] = __builtin_amdgcn_mfma_f32_16x16x32_bf16(Bt[n][k], At[m][k], acc[ai][bj][m][n], 0, 0, 0); __builtin_amdgcn_s_setprio(0); } while (0)
; #define PG8_WAIT_V(n) asm volatile("s_waitcnt vmcnt(" #n ")" ::: "memory")
; #define PG8_WAIT_L(n) asm volatile("s_waitcnt lgkmcnt(" #n ")" ::: "memory")
; #define PG8_BAR __builtin_amdgcn_s_barrier()
; #define PG8_SCHED __builtin_amdgcn_sched_barrier(0)
; template <class Epi, class Sched, bool ALIGN_EPI = false, bool SP2 = false>
; __device__ __forceinline__ void gemm_phase(PG8_LAS unsigned char* lds, const Gemm g, const Sched& S, const Epi& E) {
;     ...
;             const bool last = (t == nt - 2);
;             const char* a1 = cA + (size_t)(t + 1) * kstep;
;             const char* a2 = last ? nA : cA + (size_t)(t + 2) * kstep; const char* b2 = last ? nB : cB + (size_t)(t + 2) * kstep;
;             const char* a3 = a2 + kstep; const char* b3 = b2 + kstep;
;             if (last && has_next) S.a_ready(nxt);
;             if constexpr (SP2) {
;             PG8_LDB(B0, 0, 0); PG8_LDB(B1, 0, 1); PG8_SCHED; PG8_LDA(At, 0, 0); PG8_STAGE(PG8_SA(1, 1), a1 + hstep, voffA);
;             PG8_WAIT_V(8); PG8_WAIT_L(0); PG8_BAR; PG8_MMA(0, 0, At, B0); PG8_MMA(0, 1, At, B1); PG8_BAR; PG8_SCHED;
;             PG8_LDA(At, 0, 1); PG8_STAGE(PG8_SB(0, 0), b2, voffB); PG8_STAGE(PG8_SB(0, 1), b2 + hstep, voffB); PG8_STAGE(PG8_SA(0, 0), a2, voffA);
.LBB0_138:
	s_add_u32 s18, s50, 0xfffc0080
	s_addc_u32 s19, s51, -1
	s_add_i32 s69, 0, 0x10000
	s_cmp_eq_u32 s68, 12
	s_cselect_b32 s55, s41, s19
	s_cselect_b32 s54, s49, s18
	s_cselect_b32 s53, s21, s67
	s_cselect_b32 s52, s65, s66
	s_add_i32 s18, 0, 0x14000
	v_add_u32_e32 v140, s69, v171
	v_add_u32_e32 v166, s18, v171
	ds_read_b128 v[128:131], v140
	ds_read_b128 v[132:135], v140 offset:1024
	ds_read_b128 v[136:139], v140 offset:2048
	ds_read_b128 v[140:143], v140 offset:3072
	ds_read_b128 v[144:147], v166
	ds_read_b128 v[158:161], v166 offset:1024
	ds_read_b128 v[162:165], v166 offset:2048
	ds_read_b128 v[166:169], v166 offset:3072
	v_lshl_add_u64 v[206:207], s[50:51], 0, v[154:155]
	s_add_i32 m0, s57, 0xc000
	ds_read_b128 v[174:177], v173
	ds_read_b128 v[178:181], v173 offset:1024
	ds_read_b128 v[182:185], v173 offset:2048
	ds_read_b128 v[186:189], v173 offset:3072
	ds_read_b128 v[190:193], v173 offset:4096
	ds_read_b128 v[194:197], v173 offset:5120
	ds_read_b128 v[198:201], v173 offset:6144
	ds_read_b128 v[202:205], v173 offset:7168
	global_load_lds_dwordx4 v[206:207], off
	v_lshl_add_u64 v[206:207], s[50:51], 0, v[156:157]
	s_add_i32 m0, s57, 0xe000
	s_nop 0
	global_load_lds_dwordx4 v[206:207], off
	s_waitcnt vmcnt(8)
	s_waitcnt lgkmcnt(0)
	s_setprio 1
	s_barrier
	v_mfma_f32_16x16x32_bf16 v[124:127], v[128:131], v[174:177], v[124:127]
	v_mfma_f32_16x16x32_bf16 v[120:123], v[136:139], v[174:177], v[120:123]
	v_mfma_f32_16x16x32_bf16 v[116:119], v[128:131], v[182:185], v[116:119]
	v_mfma_f32_16x16x32_bf16 v[112:115], v[136:139], v[182:185], v[112:115]
	v_mfma_f32_16x16x32_bf16 v[96:99], v[128:131], v[190:193], v[96:99]
	v_mfma_f32_16x16x32_bf16 v[92:95], v[136:139], v[190:193], v[92:95]
	v_mfma_f32_16x16x32_bf16 v[84:87], v[128:131], v[198:201], v[84:87]
	v_mfma_f32_16x16x32_bf16 v[80:83], v[136:139], v[198:201], v[80:83]
	v_mfma_f32_16x16x32_bf16 v[124:127], v[132:135], v[178:181], v[124:127]
	v_mfma_f32_16x16x32_bf16 v[120:123], v[140:143], v[178:181], v[120:123]
	v_mfma_f32_16x16x32_bf16 v[116:119], v[132:135], v[186:189], v[116:119]
	v_mfma_f32_16x16x32_bf16 v[112:115], v[140:143], v[186:189], v[112:115]
	v_mfma_f32_16x16x32_bf16 v[96:99], v[132:135], v[194:197], v[96:99]
	v_mfma_f32_16x16x32_bf16 v[92:95], v[140:143], v[194:197], v[92:95]
	v_mfma_f32_16x16x32_bf16 v[84:87], v[132:135], v[202:205], v[84:87]
	v_mfma_f32_16x16x32_bf16 v[80:83], v[140:143], v[202:205], v[80:83]
	v_mfma_f32_16x16x32_bf16 v[108:111], v[144:147], v[174:177], v[108:111]
	v_mfma_f32_16x16x32_bf16 v[104:107], v[162:165], v[174:177], v[104:107]
	v_mfma_f32_16x16x32_bf16 v[100:103], v[144:147], v[182:185], v[100:103]
	v_mfma_f32_16x16x32_bf16 v[88:91], v[162:165], v[182:185], v[88:91]
	v_mfma_f32_16x16x32_bf16 v[76:79], v[144:147], v[190:193], v[76:79]
	v_mfma_f32_16x16x32_bf16 v[72:75], v[162:165], v[190:193], v[72:75]
	v_mfma_f32_16x16x32_bf16 v[68:71], v[144:147], v[198:201], v[68:71]
	v_mfma_f32_16x16x32_bf16 v[64:67], v[162:165], v[198:201], v[64:67]
	v_mfma_f32_16x16x32_bf16 v[108:111], v[158:161], v[178:181], v[108:111]
	v_mfma_f32_16x16x32_bf16 v[104:107], v[166:169], v[178:181], v[104:107]
	v_mfma_f32_16x16x32_bf16 v[100:103], v[158:161], v[186:189], v[100:103]
	v_mfma_f32_16x16x32_bf16 v[88:91], v[166:169], v[186:189], v[88:91]
	v_mfma_f32_16x16x32_bf16 v[76:79], v[158:161], v[194:197], v[76:79]
	v_mfma_f32_16x16x32_bf16 v[72:75], v[166:169], v[194:197], v[72:75]
	v_mfma_f32_16x16x32_bf16 v[68:71], v[158:161], v[202:205], v[68:71]
	v_mfma_f32_16x16x32_bf16 v[64:67], v[166:169], v[202:205], v[64:67]
	s_barrier
	s_setprio 0
	s_add_i32 s19, s69, s56
	v_lshl_add_u64 v[206:207], s[52:53], 0, v[208:209]
	s_mov_b32 m0, s19
	ds_read_b128 v[174:177], v173 offset:16384
	ds_read_b128 v[178:181], v173 offset:17408
	ds_read_b128 v[182:185], v173 offset:18432
	ds_read_b128 v[186:189], v173 offset:19456
	ds_read_b128 v[190:193], v173 offset:20480
	ds_read_b128 v[194:197], v173 offset:21504
	ds_read_b128 v[198:201], v173 offset:22528
	ds_read_b128 v[202:205], v173 offset:23552
	global_load_lds_dwordx4 v[206:207], off
	s_add_i32 m0, s19, 0x2000
	s_add_u32 s70, s52, 0x40000
	v_lshl_add_u64 v[212:213], s[52:53], 0, v[152:153]
	s_addc_u32 s71, s53, 0
	s_add_i32 s18, s18, s56
	global_load_lds_dwordx4 v[212:213], off
	v_lshl_add_u64 v[214:215], s[70:71], 0, v[208:209]
	s_mov_b32 m0, s18
	v_lshl_add_u64 v[218:219], s[54:55], 0, v[150:151]
	global_load_lds_dwordx4 v[214:215], off
	v_lshl_add_u64 v[214:215], s[70:71], 0, v[152:153]
	s_add_i32 m0, s18, 0x2000
	s_nop 0
	global_load_lds_dwordx4 v[214:215], off
	v_lshl_add_u64 v[214:215], s[54:55], 0, v[148:149]
	s_mov_b32 m0, s57
	s_nop 0
	global_load_lds_dwordx4 v[214:215], off
	s_mov_b32 m0, s58
	s_nop 0
	global_load_lds_dwordx4 v[218:219], off
	s_waitcnt vmcnt(8)
	s_waitcnt lgkmcnt(0)
	s_setprio 1
	s_barrier
; #define PG8_STAGE(bufoff, gbase, voff) do { _Pragma("unroll") for (int _i = 0; _i < 2; ++_i) \
;         __builtin_amdgcn_global_load_lds((const unsigned*)((const char*)(gbase) + (voff)[_i]), (PG8_LAS unsigned*)(lds + (bufoff) + ldsw + _i * 8192), 16, 0, 0); } while (0)
; #define PG8_LDA(dst, b, h) do { _Pragma("unroll") for (int m = 0; m < 4; ++m) _Pragma("unroll") for (int k = 0; k < 2; ++k) dst[m][k] = *(const PG8_LAS bf16x8*)(lds + PG8_SA(b, h) + aoff + m * 2048 + k * 1024); } while (0)
; #define PG8_LDB(dst, b, h) do { _Pragma("unroll") for (int n = 0; n < 2; ++n) _Pragma("unroll") for (int k = 0; k < 2; ++k) dst[n][k] = *(const PG8_LAS bf16x8*)(lds + PG8_SB(b, h) + boff + n * 2048 + k * 1024); } while (0)
; #define PG8_MMA(ai, bj, At, Bt) do { __builtin_amdgcn_s_setprio(1); _Pragma("unroll") for (int m = 0; m < 4; ++m) _Pragma("unroll") for (int n = 0; n < 2; ++n) _Pragma("unroll") for (int k = 0; k < 2; ++k) \
;         acc[ai][bj][m][n] = __builtin_amdgcn_mfma_f32_16x16x32_bf16(Bt[n][k], At[m][k], acc[ai][bj][m][n], 0, 0, 0); __builtin_amdgcn_s_setprio(0); } while (0)
; #define PG8_WAIT_V(n) asm volatile("s_waitcnt vmcnt(" #n ")" ::: "memory")
; #define PG8_WAIT_L(n) asm volatile("s_waitcnt lgkmcnt(" #n ")" ::: "memory")
; #define PG8_BAR __builtin_amdgcn_s_barrier()
; #define PG8_SCHED __builtin_amdgcn_sched_barrier(0)
; template <class Epi, class Sched, bool ALIGN_EPI = false, bool SP2 = false>
; __device__ __forceinline__ void gemm_phase(PG8_LAS unsigned char* lds, const Gemm g, const Sched& S, const Epi& E) {
;     ...
;             PG8_WAIT_V(8); PG8_WAIT_L(0); PG8_BAR; PG8_MMA(1, 0, At, B0); PG8_MMA(1, 1, At, B1); PG8_BAR; PG8_SCHED;
;             PG8_LDB(B0, 1, 0); PG8_LDB(B1, 1, 1); PG8_SCHED; PG8_LDA(At, 1, 0); PG8_STAGE(PG8_SA(0, 1), a2 + hstep, voffA);
;             PG8_WAIT_V(8); PG8_WAIT_L(0); PG8_BAR; PG8_MMA(0, 0, At, B0); PG8_MMA(0, 1, At, B1); PG8_BAR; PG8_SCHED;
	v_mfma_f32_16x16x32_bf16 v[60:63], v[128:131], v[174:177], v[60:63]
	v_mfma_f32_16x16x32_bf16 v[56:59], v[136:139], v[174:177], v[56:59]
	v_mfma_f32_16x16x32_bf16 v[48:51], v[128:131], v[182:185], v[48:51]
	v_mfma_f32_16x16x32_bf16 v[40:43], v[136:139], v[182:185], v[40:43]
	v_mfma_f32_16x16x32_bf16 v[32:35], v[128:131], v[190:193], v[32:35]
	v_mfma_f32_16x16x32_bf16 v[24:27], v[136:139], v[190:193], v[24:27]
	v_mfma_f32_16x16x32_bf16 v[16:19], v[128:131], v[198:201], v[16:19]
	v_mfma_f32_16x16x32_bf16 v[8:11], v[136:139], v[198:201], v[8:11]
	v_mfma_f32_16x16x32_bf16 v[60:63], v[132:135], v[178:181], v[60:63]
	v_mfma_f32_16x16x32_bf16 v[56:59], v[140:143], v[178:181], v[56:59]
	v_mfma_f32_16x16x32_bf16 v[48:51], v[132:135], v[186:189], v[48:51]
	v_mfma_f32_16x16x32_bf16 v[40:43], v[140:143], v[186:189], v[40:43]
	v_mfma_f32_16x16x32_bf16 v[32:35], v[132:135], v[194:197], v[32:35]
	v_mfma_f32_16x16x32_bf16 v[24:27], v[140:143], v[194:197], v[24:27]
	v_mfma_f32_16x16x32_bf16 v[16:19], v[132:135], v[202:205], v[16:19]
	v_mfma_f32_16x16x32_bf16 v[8:11], v[140:143], v[202:205], v[8:11]
	v_mfma_f32_16x16x32_bf16 v[52:55], v[144:147], v[174:177], v[52:55]
	v_mfma_f32_16x16x32_bf16 v[44:47], v[162:165], v[174:177], v[44:47]
	v_mfma_f32_16x16x32_bf16 v[36:39], v[144:147], v[182:185], v[36:39]
	v_mfma_f32_16x16x32_bf16 v[28:31], v[162:165], v[182:185], v[28:31]
	v_mfma_f32_16x16x32_bf16 v[20:23], v[144:147], v[190:193], v[20:23]
	v_mfma_f32_16x16x32_bf16 v[12:15], v[162:165], v[190:193], v[12:15]
	v_mfma_f32_16x16x32_bf16 v[4:7], v[144:147], v[198:201], v[4:7]
	v_mfma_f32_16x16x32_bf16 v[0:3], v[162:165], v[198:201], v[0:3]
	v_mfma_f32_16x16x32_bf16 v[52:55], v[158:161], v[178:181], v[52:55]
	v_mfma_f32_16x16x32_bf16 v[44:47], v[166:169], v[178:181], v[44:47]
	v_mfma_f32_16x16x32_bf16 v[36:39], v[158:161], v[186:189], v[36:39]
	v_mfma_f32_16x16x32_bf16 v[28:31], v[166:169], v[186:189], v[28:31]
	v_mfma_f32_16x16x32_bf16 v[20:23], v[158:161], v[194:197], v[20:23]
	v_mfma_f32_16x16x32_bf16 v[12:15], v[166:169], v[194:197], v[12:15]
	v_mfma_f32_16x16x32_bf16 v[4:7], v[158:161], v[202:205], v[4:7]
	v_mfma_f32_16x16x32_bf16 v[0:3], v[166:169], v[202:205], v[0:3]
	s_barrier
	s_setprio 0
	s_add_i32 s18, 0, 0x18000
	s_add_i32 s19, 0, 0x1c000
	v_add_u32_e32 v140, s18, v171
	v_add_u32_e32 v166, s19, v171
	ds_read_b128 v[128:131], v140
	ds_read_b128 v[132:135], v140 offset:1024
	ds_read_b128 v[136:139], v140 offset:2048
	ds_read_b128 v[140:143], v140 offset:3072
	ds_read_b128 v[144:147], v166
	ds_read_b128 v[158:161], v166 offset:1024
	ds_read_b128 v[162:165], v166 offset:2048
	ds_read_b128 v[166:169], v166 offset:3072
	s_add_u32 s54, s54, 0x40000
	s_addc_u32 s55, s55, 0
	s_mov_b32 m0, s59
	v_lshl_add_u64 v[220:221], s[54:55], 0, v[148:149]
	ds_read_b128 v[174:177], v173 offset:32768
	ds_read_b128 v[178:181], v173 offset:33792
	ds_read_b128 v[182:185], v173 offset:34816
	ds_read_b128 v[186:189], v173 offset:35840
	ds_read_b128 v[190:193], v173 offset:36864
	ds_read_b128 v[194:197], v173 offset:37888
	ds_read_b128 v[198:201], v173 offset:38912
	ds_read_b128 v[202:205], v173 offset:39936
	global_load_lds_dwordx4 v[220:221], off
	v_lshl_add_u64 v[220:221], s[54:55], 0, v[150:151]
	s_mov_b32 m0, s60
	s_nop 0
	global_load_lds_dwordx4 v[220:221], off
	s_waitcnt vmcnt(8)
	s_waitcnt lgkmcnt(0)
	s_setprio 1
	s_barrier
	v_mfma_f32_16x16x32_bf16 v[124:127], v[128:131], v[174:177], v[124:127]
	v_mfma_f32_16x16x32_bf16 v[120:123], v[136:139], v[174:177], v[120:123]
	v_mfma_f32_16x16x32_bf16 v[116:119], v[128:131], v[182:185], v[116:119]
	v_mfma_f32_16x16x32_bf16 v[112:115], v[136:139], v[182:185], v[112:115]
	v_mfma_f32_16x16x32_bf16 v[96:99], v[128:131], v[190:193], v[96:99]
	v_mfma_f32_16x16x32_bf16 v[92:95], v[136:139], v[190:193], v[92:95]
	v_mfma_f32_16x16x32_bf16 v[84:87], v[128:131], v[198:201], v[84:87]
	v_mfma_f32_16x16x32_bf16 v[80:83], v[136:139], v[198:201], v[80:83]
	v_mfma_f32_16x16x32_bf16 v[124:127], v[132:135], v[178:181], v[124:127]
	v_mfma_f32_16x16x32_bf16 v[120:123], v[140:143], v[178:181], v[120:123]
	v_mfma_f32_16x16x32_bf16 v[116:119], v[132:135], v[186:189], v[116:119]
	v_mfma_f32_16x16x32_bf16 v[112:115], v[140:143], v[186:189], v[112:115]
	v_mfma_f32_16x16x32_bf16 v[96:99], v[132:135], v[194:197], v[96:99]
	v_mfma_f32_16x16x32_bf16 v[92:95], v[140:143], v[194:197], v[92:95]
	v_mfma_f32_16x16x32_bf16 v[84:87], v[132:135], v[202:205], v[84:87]
	v_mfma_f32_16x16x32_bf16 v[80:83], v[140:143], v[202:205], v[80:83]
	v_mfma_f32_16x16x32_bf16 v[108:111], v[144:147], v[174:177], v[108:111]
	v_mfma_f32_16x16x32_bf16 v[104:107], v[162:165], v[174:177], v[104:107]
	v_mfma_f32_16x16x32_bf16 v[100:103], v[144:147], v[182:185], v[100:103]
	v_mfma_f32_16x16x32_bf16 v[88:91], v[162:165], v[182:185], v[88:91]
	v_mfma_f32_16x16x32_bf16 v[76:79], v[144:147], v[190:193], v[76:79]
	v_mfma_f32_16x16x32_bf16 v[72:75], v[162:165], v[190:193], v[72:75]
	v_mfma_f32_16x16x32_bf16 v[68:71], v[144:147], v[198:201], v[68:71]
	v_mfma_f32_16x16x32_bf16 v[64:67], v[162:165], v[198:201], v[64:67]
	v_mfma_f32_16x16x32_bf16 v[108:111], v[158:161], v[178:181], v[108:111]
	v_mfma_f32_16x16x32_bf16 v[104:107], v[166:169], v[178:181], v[104:107]
	v_mfma_f32_16x16x32_bf16 v[100:103], v[158:161], v[186:189], v[100:103]
	v_mfma_f32_16x16x32_bf16 v[88:91], v[166:169], v[186:189], v[88:91]
	v_mfma_f32_16x16x32_bf16 v[76:79], v[158:161], v[194:197], v[76:79]
	v_mfma_f32_16x16x32_bf16 v[72:75], v[166:169], v[194:197], v[72:75]
	v_mfma_f32_16x16x32_bf16 v[68:71], v[158:161], v[202:205], v[68:71]
	v_mfma_f32_16x16x32_bf16 v[64:67], v[166:169], v[202:205], v[64:67]
	s_barrier
; #define PG8_STAGE(bufoff, gbase, voff) do { _Pragma("unroll") for (int _i = 0; _i < 2; ++_i) \
;         __builtin_amdgcn_global_load_lds((const unsigned*)((const char*)(gbase) + (voff)[_i]), (PG8_LAS unsigned*)(lds + (bufoff) + ldsw + _i * 8192), 16, 0, 0); } while (0)
; #define PG8_LDA(dst, b, h) do { _Pragma("unroll") for (int m = 0; m < 4; ++m) _Pragma("unroll") for (int k = 0; k < 2; ++k) dst[m][k] = *(const PG8_LAS bf16x8*)(lds + PG8_SA(b, h) + aoff + m * 2048 + k * 1024); } while (0)
; #define PG8_MMA(ai, bj, At, Bt) do { __builtin_amdgcn_s_setprio(1); _Pragma("unroll") for (int m = 0; m < 4; ++m) _Pragma("unroll") for (int n = 0; n < 2; ++n) _Pragma("unroll") for (int k = 0; k < 2; ++k) \
;         acc[ai][bj][m][n] = __builtin_amdgcn_mfma_f32_16x16x32_bf16(Bt[n][k], At[m][k], acc[ai][bj][m][n], 0, 0, 0); __builtin_amdgcn_s_setprio(0); } while (0)
; #define PG8_WAIT_V(n) asm volatile("s_waitcnt vmcnt(" #n ")" ::: "memory")
; #define PG8_WAIT_L(n) asm volatile("s_waitcnt lgkmcnt(" #n ")" ::: "memory")
; #define PG8_BAR __builtin_amdgcn_s_barrier()
; #define PG8_SCHED __builtin_amdgcn_sched_barrier(0)
; template <class Epi, class Sched, bool ALIGN_EPI = false, bool SP2 = false>
; __device__ __forceinline__ void gemm_phase(PG8_LAS unsigned char* lds, const Gemm g, const Sched& S, const Epi& E) {
;     ...
;             PG8_LDA(At, 1, 1); PG8_STAGE(PG8_SB(1, 0), b3, voffB); PG8_STAGE(PG8_SB(1, 1), b3 + hstep, voffB); PG8_STAGE(PG8_SA(1, 0), a3, voffA);
;             PG8_WAIT_V(8); PG8_WAIT_L(0); PG8_BAR; PG8_MMA(1, 0, At, B0); PG8_MMA(1, 1, At, B1); PG8_BAR; PG8_SCHED;
;     ...
;         if constexpr (ALIGN_EPI) { if (wr == 0) PG8_BAR; }
	s_setprio 0
	s_add_i32 s18, s18, s56
	v_lshl_add_u64 v[206:207], v[206:207], 0, s[24:25]
	s_mov_b32 m0, s18
	ds_read_b128 v[174:177], v173 offset:49152
	ds_read_b128 v[178:181], v173 offset:50176
	ds_read_b128 v[182:185], v173 offset:51200
	ds_read_b128 v[186:189], v173 offset:52224
	ds_read_b128 v[190:193], v173 offset:53248
	ds_read_b128 v[194:197], v173 offset:54272
	ds_read_b128 v[198:201], v173 offset:55296
	ds_read_b128 v[202:205], v173 offset:56320
	global_load_lds_dwordx4 v[206:207], off
	s_add_i32 m0, s18, 0x2000
	s_add_u32 s52, s52, 0x40080
	v_lshl_add_u64 v[206:207], v[212:213], 0, s[24:25]
	s_addc_u32 s53, s53, 0
	s_add_i32 s18, s19, s56
	global_load_lds_dwordx4 v[206:207], off
	v_lshl_add_u64 v[206:207], s[52:53], 0, v[208:209]
	s_mov_b32 m0, s18
	s_nop 0
	global_load_lds_dwordx4 v[206:207], off
	v_lshl_add_u64 v[206:207], s[52:53], 0, v[152:153]
	s_add_i32 m0, s18, 0x2000
	s_nop 0
	global_load_lds_dwordx4 v[206:207], off
	v_lshl_add_u64 v[206:207], v[214:215], 0, s[24:25]
	s_mov_b32 m0, s61
	s_nop 0
	global_load_lds_dwordx4 v[206:207], off
	v_lshl_add_u64 v[206:207], v[218:219], 0, s[24:25]
	s_mov_b32 m0, s62
	s_nop 0
	global_load_lds_dwordx4 v[206:207], off
	s_waitcnt vmcnt(8)
	s_waitcnt lgkmcnt(0)
	s_setprio 1
	s_barrier
	v_mfma_f32_16x16x32_bf16 v[60:63], v[128:131], v[174:177], v[60:63]
	v_mfma_f32_16x16x32_bf16 v[56:59], v[136:139], v[174:177], v[56:59]
	v_mfma_f32_16x16x32_bf16 v[48:51], v[128:131], v[182:185], v[48:51]
	v_mfma_f32_16x16x32_bf16 v[40:43], v[136:139], v[182:185], v[40:43]
	v_mfma_f32_16x16x32_bf16 v[32:35], v[128:131], v[190:193], v[32:35]
	v_mfma_f32_16x16x32_bf16 v[24:27], v[136:139], v[190:193], v[24:27]
	v_mfma_f32_16x16x32_bf16 v[16:19], v[128:131], v[198:201], v[16:19]
	v_mfma_f32_16x16x32_bf16 v[8:11], v[136:139], v[198:201], v[8:11]
	v_mfma_f32_16x16x32_bf16 v[60:63], v[132:135], v[178:181], v[60:63]
	v_mfma_f32_16x16x32_bf16 v[56:59], v[140:143], v[178:181], v[56:59]
	v_mfma_f32_16x16x32_bf16 v[48:51], v[132:135], v[186:189], v[48:51]
	v_mfma_f32_16x16x32_bf16 v[40:43], v[140:143], v[186:189], v[40:43]
	v_mfma_f32_16x16x32_bf16 v[32:35], v[132:135], v[194:197], v[32:35]
	v_mfma_f32_16x16x32_bf16 v[24:27], v[140:143], v[194:197], v[24:27]
	v_mfma_f32_16x16x32_bf16 v[16:19], v[132:135], v[202:205], v[16:19]
	v_mfma_f32_16x16x32_bf16 v[8:11], v[140:143], v[202:205], v[8:11]
	v_mfma_f32_16x16x32_bf16 v[52:55], v[144:147], v[174:177], v[52:55]
	v_mfma_f32_16x16x32_bf16 v[44:47], v[162:165], v[174:177], v[44:47]
	v_mfma_f32_16x16x32_bf16 v[36:39], v[144:147], v[182:185], v[36:39]
	v_mfma_f32_16x16x32_bf16 v[28:31], v[162:165], v[182:185], v[28:31]
	v_mfma_f32_16x16x32_bf16 v[20:23], v[144:147], v[190:193], v[20:23]
	v_mfma_f32_16x16x32_bf16 v[12:15], v[162:165], v[190:193], v[12:15]
	v_mfma_f32_16x16x32_bf16 v[4:7], v[144:147], v[198:201], v[4:7]
	v_mfma_f32_16x16x32_bf16 v[0:3], v[162:165], v[198:201], v[0:3]
	v_mfma_f32_16x16x32_bf16 v[52:55], v[158:161], v[178:181], v[52:55]
	v_mfma_f32_16x16x32_bf16 v[44:47], v[166:169], v[178:181], v[44:47]
	v_mfma_f32_16x16x32_bf16 v[36:39], v[158:161], v[186:189], v[36:39]
	v_mfma_f32_16x16x32_bf16 v[28:31], v[166:169], v[186:189], v[28:31]
	v_mfma_f32_16x16x32_bf16 v[20:23], v[158:161], v[194:197], v[20:23]
	v_mfma_f32_16x16x32_bf16 v[12:15], v[166:169], v[194:197], v[12:15]
	v_mfma_f32_16x16x32_bf16 v[4:7], v[158:161], v[202:205], v[4:7]
	v_mfma_f32_16x16x32_bf16 v[0:3], v[166:169], v[202:205], v[0:3]
	s_barrier
	s_setprio 0
	s_add_i32 s68, s68, 2
	s_add_u32 s50, s50, 0x100
	s_addc_u32 s51, s51, 0
	s_add_u32 s66, s66, 0x100
	s_addc_u32 s67, s67, 0
	s_cmp_gt_u32 s68, 13
	s_cbranch_scc0 .LBB0_138
	s_and_b64 vcc, exec, s[8:9]
	s_cbranch_vccz .LBB0_141
	s_barrier

; #define PG8_STAGE(bufoff, gbase, voff) do { _Pragma("unroll") for (int _i = 0; _i < 2; ++_i) \
;         __builtin_amdgcn_global_load_lds((const unsigned*)((const char*)(gbase) + (voff)[_i]), (PG8_LAS unsigned*)(lds + (bufoff) + ldsw + _i * 8192), 16, 0, 0); } while (0)
; #define PG8_LDA(dst, b, h) do { _Pragma("unroll") for (int m = 0; m < 4; ++m) _Pragma("unroll") for (int k = 0; k < 2; ++k) dst[m][k] = *(const PG8_LAS bf16x8*)(lds + PG8_SA(b, h) + aoff + m * 2048 + k * 1024); } while (0)
; #define PG8_LDB(dst, b, h) do { _Pragma("unroll") for (int n = 0; n < 2; ++n) _Pragma("unroll") for (int k = 0; k < 2; ++k) dst[n][k] = *(const PG8_LAS bf16x8*)(lds + PG8_SB(b, h) + boff + n * 2048 + k * 1024); } while (0)
; #define PG8_MMA(ai, bj, At, Bt) do { __builtin_amdgcn_s_setprio(1); _Pragma("unroll") for (int m = 0; m < 4; ++m) _Pragma("unroll") for (int n = 0; n < 2; ++n) _Pragma("unroll") for (int k = 0; k < 2; ++k) \
;         acc[ai][bj][m][n] = __builtin_amdgcn_mfma_f32_16x16x32_bf16(Bt[n][k], At[m][k], acc[ai][bj][m][n], 0, 0, 0); __builtin_amdgcn_s_setprio(0); } while (0)
; #define PG8_WAIT_V(n) asm volatile("s_waitcnt vmcnt(" #n ")" ::: "memory")
; #define PG8_WAIT_L(n) asm volatile("s_waitcnt lgkmcnt(" #n ")" ::: "memory")
; #define PG8_BAR __builtin_amdgcn_s_barrier()
; #define PG8_SCHED __builtin_amdgcn_sched_barrier(0)
; template <class Epi, class Sched, bool ALIGN_EPI = false, bool SP2 = false>
; __device__ __forceinline__ void gemm_phase(PG8_LAS unsigned char* lds, const Gemm g, const Sched& S, const Epi& E) {
;     ...
;             const bool last = (t == nt - 2);
;             const char* a1 = cA + (size_t)(t + 1) * kstep;
;             const char* a2 = last ? nA : cA + (size_t)(t + 2) * kstep; const char* b2 = last ? nB : cB + (size_t)(t + 2) * kstep;
;             const char* a3 = a2 + kstep; const char* b3 = b2 + kstep;
;             if (last && has_next) S.a_ready(nxt);
;             if constexpr (SP2) {
;             PG8_LDB(B0, 0, 0); PG8_LDB(B1, 0, 1); PG8_SCHED; PG8_LDA(At, 0, 0); PG8_STAGE(PG8_SA(1, 1), a1 + hstep, voffA);
;             PG8_WAIT_V(8); PG8_WAIT_L(0); PG8_BAR; PG8_MMA(0, 0, At, B0); PG8_MMA(0, 1, At, B1); PG8_BAR; PG8_SCHED;
;             PG8_LDA(At, 0, 1); PG8_STAGE(PG8_SB(0, 0), b2, voffB); PG8_STAGE(PG8_SB(0, 1), b2 + hstep, voffB); PG8_STAGE(PG8_SA(0, 0), a2, voffA);
.LBB0_162:
	s_add_u32 s18, s48, 0xfffc0080
	s_addc_u32 s19, s49, -1
	s_add_i32 s67, 0, 0x10000
	s_cmp_eq_u32 s66, 12
	s_cselect_b32 s53, s21, s19
	s_cselect_b32 s52, s47, s18
	s_cselect_b32 s51, s9, s65
	s_cselect_b32 s50, s63, s64
	s_add_i32 s18, 0, 0x14000
	v_add_u32_e32 v140, s67, v205
	v_add_u32_e32 v156, s18, v205
	ds_read_b128 v[128:131], v140
	ds_read_b128 v[132:135], v140 offset:1024
	ds_read_b128 v[136:139], v140 offset:2048
	ds_read_b128 v[140:143], v140 offset:3072
	ds_read_b128 v[144:147], v156
	ds_read_b128 v[148:151], v156 offset:1024
	ds_read_b128 v[152:155], v156 offset:2048
	ds_read_b128 v[156:159], v156 offset:3072
	v_lshl_add_u64 v[202:203], s[48:49], 0, v[190:191]
	s_add_i32 m0, s55, 0xc000
	ds_read_b128 v[160:163], v207
	ds_read_b128 v[164:167], v207 offset:1024
	ds_read_b128 v[168:171], v207 offset:2048
	ds_read_b128 v[172:175], v207 offset:3072
	ds_read_b128 v[176:179], v207 offset:4096
	ds_read_b128 v[180:183], v207 offset:5120
	ds_read_b128 v[194:197], v207 offset:6144
	ds_read_b128 v[198:201], v207 offset:7168
	global_load_lds_dwordx4 v[202:203], off
	v_lshl_add_u64 v[202:203], s[48:49], 0, v[192:193]
	s_add_i32 m0, s55, 0xe000
	s_nop 0
	global_load_lds_dwordx4 v[202:203], off
	s_waitcnt vmcnt(8)
	s_waitcnt lgkmcnt(0)
	s_setprio 1
	s_barrier
	v_mfma_f32_16x16x32_bf16 v[124:127], v[128:131], v[160:163], v[124:127]
	v_mfma_f32_16x16x32_bf16 v[120:123], v[136:139], v[160:163], v[120:123]
	v_mfma_f32_16x16x32_bf16 v[108:111], v[128:131], v[168:171], v[108:111]
	v_mfma_f32_16x16x32_bf16 v[104:107], v[136:139], v[168:171], v[104:107]
	v_mfma_f32_16x16x32_bf16 v[92:95], v[128:131], v[176:179], v[92:95]
	v_mfma_f32_16x16x32_bf16 v[88:91], v[136:139], v[176:179], v[88:91]
	v_mfma_f32_16x16x32_bf16 v[76:79], v[128:131], v[194:197], v[76:79]
	v_mfma_f32_16x16x32_bf16 v[72:75], v[136:139], v[194:197], v[72:75]
	v_mfma_f32_16x16x32_bf16 v[124:127], v[132:135], v[164:167], v[124:127]
	v_mfma_f32_16x16x32_bf16 v[120:123], v[140:143], v[164:167], v[120:123]
	v_mfma_f32_16x16x32_bf16 v[108:111], v[132:135], v[172:175], v[108:111]
	v_mfma_f32_16x16x32_bf16 v[104:107], v[140:143], v[172:175], v[104:107]
	v_mfma_f32_16x16x32_bf16 v[92:95], v[132:135], v[180:183], v[92:95]
	v_mfma_f32_16x16x32_bf16 v[88:91], v[140:143], v[180:183], v[88:91]
	v_mfma_f32_16x16x32_bf16 v[76:79], v[132:135], v[198:201], v[76:79]
	v_mfma_f32_16x16x32_bf16 v[72:75], v[140:143], v[198:201], v[72:75]
	v_mfma_f32_16x16x32_bf16 v[116:119], v[144:147], v[160:163], v[116:119]
	v_mfma_f32_16x16x32_bf16 v[112:115], v[152:155], v[160:163], v[112:115]
	v_mfma_f32_16x16x32_bf16 v[100:103], v[144:147], v[168:171], v[100:103]
	v_mfma_f32_16x16x32_bf16 v[96:99], v[152:155], v[168:171], v[96:99]
	v_mfma_f32_16x16x32_bf16 v[84:87], v[144:147], v[176:179], v[84:87]
	v_mfma_f32_16x16x32_bf16 v[80:83], v[152:155], v[176:179], v[80:83]
	v_mfma_f32_16x16x32_bf16 v[68:71], v[144:147], v[194:197], v[68:71]
	v_mfma_f32_16x16x32_bf16 v[64:67], v[152:155], v[194:197], v[64:67]
	v_mfma_f32_16x16x32_bf16 v[116:119], v[148:151], v[164:167], v[116:119]
	v_mfma_f32_16x16x32_bf16 v[112:115], v[156:159], v[164:167], v[112:115]
	v_mfma_f32_16x16x32_bf16 v[100:103], v[148:151], v[172:175], v[100:103]
	v_mfma_f32_16x16x32_bf16 v[96:99], v[156:159], v[172:175], v[96:99]
	v_mfma_f32_16x16x32_bf16 v[84:87], v[148:151], v[180:183], v[84:87]
	v_mfma_f32_16x16x32_bf16 v[80:83], v[156:159], v[180:183], v[80:83]
	v_mfma_f32_16x16x32_bf16 v[68:71], v[148:151], v[198:201], v[68:71]
	v_mfma_f32_16x16x32_bf16 v[64:67], v[156:159], v[198:201], v[64:67]
	s_barrier
	s_setprio 0
	s_add_i32 s19, s67, s54
	v_lshl_add_u64 v[202:203], s[50:51], 0, v[208:209]
	s_mov_b32 m0, s19
	ds_read_b128 v[160:163], v207 offset:16384
	ds_read_b128 v[164:167], v207 offset:17408
	ds_read_b128 v[168:171], v207 offset:18432
	ds_read_b128 v[172:175], v207 offset:19456
	ds_read_b128 v[176:179], v207 offset:20480
	ds_read_b128 v[180:183], v207 offset:21504
	ds_read_b128 v[194:197], v207 offset:22528
	ds_read_b128 v[198:201], v207 offset:23552
	global_load_lds_dwordx4 v[202:203], off
	s_add_i32 m0, s19, 0x2000
	s_add_u32 s68, s50, 0x40000
	v_lshl_add_u64 v[212:213], s[50:51], 0, v[188:189]
	s_addc_u32 s69, s51, 0
	s_add_i32 s18, s18, s54
	global_load_lds_dwordx4 v[212:213], off
	v_lshl_add_u64 v[214:215], s[68:69], 0, v[208:209]
	s_mov_b32 m0, s18
	v_lshl_add_u64 v[218:219], s[52:53], 0, v[186:187]
	global_load_lds_dwordx4 v[214:215], off
	v_lshl_add_u64 v[214:215], s[68:69], 0, v[188:189]
	s_add_i32 m0, s18, 0x2000
	s_nop 0
	global_load_lds_dwordx4 v[214:215], off
	v_lshl_add_u64 v[214:215], s[52:53], 0, v[184:185]
	s_mov_b32 m0, s55
	s_nop 0
	global_load_lds_dwordx4 v[214:215], off
	s_mov_b32 m0, s56
	s_nop 0
	global_load_lds_dwordx4 v[218:219], off
	s_waitcnt vmcnt(8)
	s_waitcnt lgkmcnt(0)
	s_setprio 1
	s_barrier
; #define PG8_STAGE(bufoff, gbase, voff) do { _Pragma("unroll") for (int _i = 0; _i < 2; ++_i) \
;         __builtin_amdgcn_global_load_lds((const unsigned*)((const char*)(gbase) + (voff)[_i]), (PG8_LAS unsigned*)(lds + (bufoff) + ldsw + _i * 8192), 16, 0, 0); } while (0)
; #define PG8_LDA(dst, b, h) do { _Pragma("unroll") for (int m = 0; m < 4; ++m) _Pragma("unroll") for (int k = 0; k < 2; ++k) dst[m][k] = *(const PG8_LAS bf16x8*)(lds + PG8_SA(b, h) + aoff + m * 2048 + k * 1024); } while (0)
; #define PG8_LDB(dst, b, h) do { _Pragma("unroll") for (int n = 0; n < 2; ++n) _Pragma("unroll") for (int k = 0; k < 2; ++k) dst[n][k] = *(const PG8_LAS bf16x8*)(lds + PG8_SB(b, h) + boff + n * 2048 + k * 1024); } while (0)
; #define PG8_MMA(ai, bj, At, Bt) do { __builtin_amdgcn_s_setprio(1); _Pragma("unroll") for (int m = 0; m < 4; ++m) _Pragma("unroll") for (int n = 0; n < 2; ++n) _Pragma("unroll") for (int k = 0; k < 2; ++k) \
;         acc[ai][bj][m][n] = __builtin_amdgcn_mfma_f32_16x16x32_bf16(Bt[n][k], At[m][k], acc[ai][bj][m][n], 0, 0, 0); __builtin_amdgcn_s_setprio(0); } while (0)
; #define PG8_WAIT_V(n) asm volatile("s_waitcnt vmcnt(" #n ")" ::: "memory")
; #define PG8_WAIT_L(n) asm volatile("s_waitcnt lgkmcnt(" #n ")" ::: "memory")
; #define PG8_BAR __builtin_amdgcn_s_barrier()
; #define PG8_SCHED __builtin_amdgcn_sched_barrier(0)
; template <class Epi, class Sched, bool ALIGN_EPI = false, bool SP2 = false>
; __device__ __forceinline__ void gemm_phase(PG8_LAS unsigned char* lds, const Gemm g, const Sched& S, const Epi& E) {
;     ...
;             PG8_WAIT_V(8); PG8_WAIT_L(0); PG8_BAR; PG8_MMA(1, 0, At, B0); PG8_MMA(1, 1, At, B1); PG8_BAR; PG8_SCHED;
;             PG8_LDB(B0, 1, 0); PG8_LDB(B1, 1, 1); PG8_SCHED; PG8_LDA(At, 1, 0); PG8_STAGE(PG8_SA(0, 1), a2 + hstep, voffA);
;             PG8_WAIT_V(8); PG8_WAIT_L(0); PG8_BAR; PG8_MMA(0, 0, At, B0); PG8_MMA(0, 1, At, B1); PG8_BAR; PG8_SCHED;
	v_mfma_f32_16x16x32_bf16 v[60:63], v[128:131], v[160:163], v[60:63]
	v_mfma_f32_16x16x32_bf16 v[56:59], v[136:139], v[160:163], v[56:59]
	v_mfma_f32_16x16x32_bf16 v[44:47], v[128:131], v[168:171], v[44:47]
	v_mfma_f32_16x16x32_bf16 v[40:43], v[136:139], v[168:171], v[40:43]
	v_mfma_f32_16x16x32_bf16 v[28:31], v[128:131], v[176:179], v[28:31]
	v_mfma_f32_16x16x32_bf16 v[24:27], v[136:139], v[176:179], v[24:27]
	v_mfma_f32_16x16x32_bf16 v[12:15], v[128:131], v[194:197], v[12:15]
	v_mfma_f32_16x16x32_bf16 v[8:11], v[136:139], v[194:197], v[8:11]
	v_mfma_f32_16x16x32_bf16 v[60:63], v[132:135], v[164:167], v[60:63]
	v_mfma_f32_16x16x32_bf16 v[56:59], v[140:143], v[164:167], v[56:59]
	v_mfma_f32_16x16x32_bf16 v[44:47], v[132:135], v[172:175], v[44:47]
	v_mfma_f32_16x16x32_bf16 v[40:43], v[140:143], v[172:175], v[40:43]
	v_mfma_f32_16x16x32_bf16 v[28:31], v[132:135], v[180:183], v[28:31]
	v_mfma_f32_16x16x32_bf16 v[24:27], v[140:143], v[180:183], v[24:27]
	v_mfma_f32_16x16x32_bf16 v[12:15], v[132:135], v[198:201], v[12:15]
	v_mfma_f32_16x16x32_bf16 v[8:11], v[140:143], v[198:201], v[8:11]
	v_mfma_f32_16x16x32_bf16 v[52:55], v[144:147], v[160:163], v[52:55]
	v_mfma_f32_16x16x32_bf16 v[48:51], v[152:155], v[160:163], v[48:51]
	v_mfma_f32_16x16x32_bf16 v[36:39], v[144:147], v[168:171], v[36:39]
	v_mfma_f32_16x16x32_bf16 v[32:35], v[152:155], v[168:171], v[32:35]
	v_mfma_f32_16x16x32_bf16 v[20:23], v[144:147], v[176:179], v[20:23]
	v_mfma_f32_16x16x32_bf16 v[16:19], v[152:155], v[176:179], v[16:19]
	v_mfma_f32_16x16x32_bf16 v[4:7], v[144:147], v[194:197], v[4:7]
	v_mfma_f32_16x16x32_bf16 v[0:3], v[152:155], v[194:197], v[0:3]
	v_mfma_f32_16x16x32_bf16 v[52:55], v[148:151], v[164:167], v[52:55]
	v_mfma_f32_16x16x32_bf16 v[48:51], v[156:159], v[164:167], v[48:51]
	v_mfma_f32_16x16x32_bf16 v[36:39], v[148:151], v[172:175], v[36:39]
	v_mfma_f32_16x16x32_bf16 v[32:35], v[156:159], v[172:175], v[32:35]
	v_mfma_f32_16x16x32_bf16 v[20:23], v[148:151], v[180:183], v[20:23]
	v_mfma_f32_16x16x32_bf16 v[16:19], v[156:159], v[180:183], v[16:19]
	v_mfma_f32_16x16x32_bf16 v[4:7], v[148:151], v[198:201], v[4:7]
	v_mfma_f32_16x16x32_bf16 v[0:3], v[156:159], v[198:201], v[0:3]
	s_barrier
	s_setprio 0
	s_add_i32 s18, 0, 0x18000
	s_add_i32 s19, 0, 0x1c000
	v_add_u32_e32 v140, s18, v205
	v_add_u32_e32 v156, s19, v205
	ds_read_b128 v[128:131], v140
	ds_read_b128 v[132:135], v140 offset:1024
	ds_read_b128 v[136:139], v140 offset:2048
	ds_read_b128 v[140:143], v140 offset:3072
	ds_read_b128 v[144:147], v156
	ds_read_b128 v[148:151], v156 offset:1024
	ds_read_b128 v[152:155], v156 offset:2048
	ds_read_b128 v[156:159], v156 offset:3072
	s_add_u32 s52, s52, 0x40000
	s_addc_u32 s53, s53, 0
	s_mov_b32 m0, s57
	v_lshl_add_u64 v[220:221], s[52:53], 0, v[184:185]
	ds_read_b128 v[160:163], v207 offset:32768
	ds_read_b128 v[164:167], v207 offset:33792
	ds_read_b128 v[168:171], v207 offset:34816
	ds_read_b128 v[172:175], v207 offset:35840
	ds_read_b128 v[176:179], v207 offset:36864
	ds_read_b128 v[180:183], v207 offset:37888
	ds_read_b128 v[194:197], v207 offset:38912
	ds_read_b128 v[198:201], v207 offset:39936
	global_load_lds_dwordx4 v[220:221], off
	v_lshl_add_u64 v[220:221], s[52:53], 0, v[186:187]
	s_mov_b32 m0, s58
	s_nop 0
	global_load_lds_dwordx4 v[220:221], off
	s_waitcnt vmcnt(8)
	s_waitcnt lgkmcnt(0)
	s_setprio 1
	s_barrier
	v_mfma_f32_16x16x32_bf16 v[124:127], v[128:131], v[160:163], v[124:127]
	v_mfma_f32_16x16x32_bf16 v[120:123], v[136:139], v[160:163], v[120:123]
	v_mfma_f32_16x16x32_bf16 v[108:111], v[128:131], v[168:171], v[108:111]
	v_mfma_f32_16x16x32_bf16 v[104:107], v[136:139], v[168:171], v[104:107]
	v_mfma_f32_16x16x32_bf16 v[92:95], v[128:131], v[176:179], v[92:95]
	v_mfma_f32_16x16x32_bf16 v[88:91], v[136:139], v[176:179], v[88:91]
	v_mfma_f32_16x16x32_bf16 v[76:79], v[128:131], v[194:197], v[76:79]
	v_mfma_f32_16x16x32_bf16 v[72:75], v[136:139], v[194:197], v[72:75]
	v_mfma_f32_16x16x32_bf16 v[124:127], v[132:135], v[164:167], v[124:127]
	v_mfma_f32_16x16x32_bf16 v[120:123], v[140:143], v[164:167], v[120:123]
	v_mfma_f32_16x16x32_bf16 v[108:111], v[132:135], v[172:175], v[108:111]
	v_mfma_f32_16x16x32_bf16 v[104:107], v[140:143], v[172:175], v[104:107]
	v_mfma_f32_16x16x32_bf16 v[92:95], v[132:135], v[180:183], v[92:95]
	v_mfma_f32_16x16x32_bf16 v[88:91], v[140:143], v[180:183], v[88:91]
	v_mfma_f32_16x16x32_bf16 v[76:79], v[132:135], v[198:201], v[76:79]
	v_mfma_f32_16x16x32_bf16 v[72:75], v[140:143], v[198:201], v[72:75]
	v_mfma_f32_16x16x32_bf16 v[116:119], v[144:147], v[160:163], v[116:119]
	v_mfma_f32_16x16x32_bf16 v[112:115], v[152:155], v[160:163], v[112:115]
	v_mfma_f32_16x16x32_bf16 v[100:103], v[144:147], v[168:171], v[100:103]
	v_mfma_f32_16x16x32_bf16 v[96:99], v[152:155], v[168:171], v[96:99]
	v_mfma_f32_16x16x32_bf16 v[84:87], v[144:147], v[176:179], v[84:87]
	v_mfma_f32_16x16x32_bf16 v[80:83], v[152:155], v[176:179], v[80:83]
	v_mfma_f32_16x16x32_bf16 v[68:71], v[144:147], v[194:197], v[68:71]
	v_mfma_f32_16x16x32_bf16 v[64:67], v[152:155], v[194:197], v[64:67]
	v_mfma_f32_16x16x32_bf16 v[116:119], v[148:151], v[164:167], v[116:119]
	v_mfma_f32_16x16x32_bf16 v[112:115], v[156:159], v[164:167], v[112:115]
	v_mfma_f32_16x16x32_bf16 v[100:103], v[148:151], v[172:175], v[100:103]
	v_mfma_f32_16x16x32_bf16 v[96:99], v[156:159], v[172:175], v[96:99]
	v_mfma_f32_16x16x32_bf16 v[84:87], v[148:151], v[180:183], v[84:87]
	v_mfma_f32_16x16x32_bf16 v[80:83], v[156:159], v[180:183], v[80:83]
	v_mfma_f32_16x16x32_bf16 v[68:71], v[148:151], v[198:201], v[68:71]
	v_mfma_f32_16x16x32_bf16 v[64:67], v[156:159], v[198:201], v[64:67]
	s_barrier
; #define PG8_STAGE(bufoff, gbase, voff) do { _Pragma("unroll") for (int _i = 0; _i < 2; ++_i) \
;         __builtin_amdgcn_global_load_lds((const unsigned*)((const char*)(gbase) + (voff)[_i]), (PG8_LAS unsigned*)(lds + (bufoff) + ldsw + _i * 8192), 16, 0, 0); } while (0)
; #define PG8_LDA(dst, b, h) do { _Pragma("unroll") for (int m = 0; m < 4; ++m) _Pragma("unroll") for (int k = 0; k < 2; ++k) dst[m][k] = *(const PG8_LAS bf16x8*)(lds + PG8_SA(b, h) + aoff + m * 2048 + k * 1024); } while (0)
; #define PG8_MMA(ai, bj, At, Bt) do { __builtin_amdgcn_s_setprio(1); _Pragma("unroll") for (int m = 0; m < 4; ++m) _Pragma("unroll") for (int n = 0; n < 2; ++n) _Pragma("unroll") for (int k = 0; k < 2; ++k) \
;         acc[ai][bj][m][n] = __builtin_amdgcn_mfma_f32_16x16x32_bf16(Bt[n][k], At[m][k], acc[ai][bj][m][n], 0, 0, 0); __builtin_amdgcn_s_setprio(0); } while (0)
; #define PG8_WAIT_V(n) asm volatile("s_waitcnt vmcnt(" #n ")" ::: "memory")
; #define PG8_WAIT_L(n) asm volatile("s_waitcnt lgkmcnt(" #n ")" ::: "memory")
; #define PG8_BAR __builtin_amdgcn_s_barrier()
; #define PG8_SCHED __builtin_amdgcn_sched_barrier(0)
; template <class Epi, class Sched, bool ALIGN_EPI = false, bool SP2 = false>
; __device__ __forceinline__ void gemm_phase(PG8_LAS unsigned char* lds, const Gemm g, const Sched& S, const Epi& E) {
;     ...
;             PG8_LDA(At, 1, 1); PG8_STAGE(PG8_SB(1, 0), b3, voffB); PG8_STAGE(PG8_SB(1, 1), b3 + hstep, voffB); PG8_STAGE(PG8_SA(1, 0), a3, voffA);
;             PG8_WAIT_V(8); PG8_WAIT_L(0); PG8_BAR; PG8_MMA(1, 0, At, B0); PG8_MMA(1, 1, At, B1); PG8_BAR; PG8_SCHED;
;     ...
;         if constexpr (ALIGN_EPI) { if (wr == 0) PG8_BAR; }
	s_setprio 0
	s_add_i32 s18, s18, s54
	v_lshl_add_u64 v[202:203], v[202:203], 0, s[24:25]
	s_mov_b32 m0, s18
	ds_read_b128 v[160:163], v207 offset:49152
	ds_read_b128 v[164:167], v207 offset:50176
	ds_read_b128 v[168:171], v207 offset:51200
	ds_read_b128 v[172:175], v207 offset:52224
	ds_read_b128 v[176:179], v207 offset:53248
	ds_read_b128 v[180:183], v207 offset:54272
	ds_read_b128 v[194:197], v207 offset:55296
	ds_read_b128 v[198:201], v207 offset:56320
	global_load_lds_dwordx4 v[202:203], off
	s_add_i32 m0, s18, 0x2000
	s_add_u32 s50, s50, 0x40080
	v_lshl_add_u64 v[202:203], v[212:213], 0, s[24:25]
	s_addc_u32 s51, s51, 0
	s_add_i32 s18, s19, s54
	global_load_lds_dwordx4 v[202:203], off
	v_lshl_add_u64 v[202:203], s[50:51], 0, v[208:209]
	s_mov_b32 m0, s18
	s_nop 0
	global_load_lds_dwordx4 v[202:203], off
	v_lshl_add_u64 v[202:203], s[50:51], 0, v[188:189]
	s_add_i32 m0, s18, 0x2000
	s_nop 0
	global_load_lds_dwordx4 v[202:203], off
	v_lshl_add_u64 v[202:203], v[214:215], 0, s[24:25]
	s_mov_b32 m0, s59
	s_nop 0
	global_load_lds_dwordx4 v[202:203], off
	v_lshl_add_u64 v[202:203], v[218:219], 0, s[24:25]
	s_mov_b32 m0, s60
	s_nop 0
	global_load_lds_dwordx4 v[202:203], off
	s_waitcnt vmcnt(8)
	s_waitcnt lgkmcnt(0)
	s_setprio 1
	s_barrier
	v_mfma_f32_16x16x32_bf16 v[60:63], v[128:131], v[160:163], v[60:63]
	v_mfma_f32_16x16x32_bf16 v[56:59], v[136:139], v[160:163], v[56:59]
	v_mfma_f32_16x16x32_bf16 v[44:47], v[128:131], v[168:171], v[44:47]
	v_mfma_f32_16x16x32_bf16 v[40:43], v[136:139], v[168:171], v[40:43]
	v_mfma_f32_16x16x32_bf16 v[28:31], v[128:131], v[176:179], v[28:31]
	v_mfma_f32_16x16x32_bf16 v[24:27], v[136:139], v[176:179], v[24:27]
	v_mfma_f32_16x16x32_bf16 v[12:15], v[128:131], v[194:197], v[12:15]
	v_mfma_f32_16x16x32_bf16 v[8:11], v[136:139], v[194:197], v[8:11]
	v_mfma_f32_16x16x32_bf16 v[60:63], v[132:135], v[164:167], v[60:63]
	v_mfma_f32_16x16x32_bf16 v[56:59], v[140:143], v[164:167], v[56:59]
	v_mfma_f32_16x16x32_bf16 v[44:47], v[132:135], v[172:175], v[44:47]
	v_mfma_f32_16x16x32_bf16 v[40:43], v[140:143], v[172:175], v[40:43]
	v_mfma_f32_16x16x32_bf16 v[28:31], v[132:135], v[180:183], v[28:31]
	v_mfma_f32_16x16x32_bf16 v[24:27], v[140:143], v[180:183], v[24:27]
	v_mfma_f32_16x16x32_bf16 v[12:15], v[132:135], v[198:201], v[12:15]
	v_mfma_f32_16x16x32_bf16 v[8:11], v[140:143], v[198:201], v[8:11]
	v_mfma_f32_16x16x32_bf16 v[52:55], v[144:147], v[160:163], v[52:55]
	v_mfma_f32_16x16x32_bf16 v[48:51], v[152:155], v[160:163], v[48:51]
	v_mfma_f32_16x16x32_bf16 v[36:39], v[144:147], v[168:171], v[36:39]
	v_mfma_f32_16x16x32_bf16 v[32:35], v[152:155], v[168:171], v[32:35]
	v_mfma_f32_16x16x32_bf16 v[20:23], v[144:147], v[176:179], v[20:23]
	v_mfma_f32_16x16x32_bf16 v[16:19], v[152:155], v[176:179], v[16:19]
	v_mfma_f32_16x16x32_bf16 v[4:7], v[144:147], v[194:197], v[4:7]
	v_mfma_f32_16x16x32_bf16 v[0:3], v[152:155], v[194:197], v[0:3]
	v_mfma_f32_16x16x32_bf16 v[52:55], v[148:151], v[164:167], v[52:55]
	v_mfma_f32_16x16x32_bf16 v[48:51], v[156:159], v[164:167], v[48:51]
	v_mfma_f32_16x16x32_bf16 v[36:39], v[148:151], v[172:175], v[36:39]
	v_mfma_f32_16x16x32_bf16 v[32:35], v[156:159], v[172:175], v[32:35]
	v_mfma_f32_16x16x32_bf16 v[20:23], v[148:151], v[180:183], v[20:23]
	v_mfma_f32_16x16x32_bf16 v[16:19], v[156:159], v[180:183], v[16:19]
	v_mfma_f32_16x16x32_bf16 v[4:7], v[148:151], v[198:201], v[4:7]
	v_mfma_f32_16x16x32_bf16 v[0:3], v[156:159], v[198:201], v[0:3]
	s_barrier
	s_setprio 0
	s_add_i32 s66, s66, 2
	s_add_u32 s48, s48, 0x100
	s_addc_u32 s49, s49, 0
	s_add_u32 s64, s64, 0x100
	s_addc_u32 s65, s65, 0
	s_cmp_gt_u32 s66, 13
	s_cbranch_scc0 .LBB0_162
	s_and_b64 vcc, exec, s[6:7]
	s_cbranch_vccz .LBB0_165
	s_barrier

; #define PG8_STAGE(bufoff, gbase, voff) do { _Pragma("unroll") for (int _i = 0; _i < 2; ++_i) \
;         __builtin_amdgcn_global_load_lds((const unsigned*)((const char*)(gbase) + (voff)[_i]), (PG8_LAS unsigned*)(lds + (bufoff) + ldsw + _i * 8192), 16, 0, 0); } while (0)
; #define PG8_LDA(dst, b, h) do { _Pragma("unroll") for (int m = 0; m < 4; ++m) _Pragma("unroll") for (int k = 0; k < 2; ++k) dst[m][k] = *(const PG8_LAS bf16x8*)(lds + PG8_SA(b, h) + aoff + m * 2048 + k * 1024); } while (0)
; #define PG8_LDB(dst, b, h) do { _Pragma("unroll") for (int n = 0; n < 2; ++n) _Pragma("unroll") for (int k = 0; k < 2; ++k) dst[n][k] = *(const PG8_LAS bf16x8*)(lds + PG8_SB(b, h) + boff + n * 2048 + k * 1024); } while (0)
; #define PG8_MMA(ai, bj, At, Bt) do { __builtin_amdgcn_s_setprio(1); _Pragma("unroll") for (int m = 0; m < 4; ++m) _Pragma("unroll") for (int n = 0; n < 2; ++n) _Pragma("unroll") for (int k = 0; k < 2; ++k) \
;         acc[ai][bj][m][n] = __builtin_amdgcn_mfma_f32_16x16x32_bf16(Bt[n][k], At[m][k], acc[ai][bj][m][n], 0, 0, 0); __builtin_amdgcn_s_setprio(0); } while (0)
; #define PG8_WAIT_V(n) asm volatile("s_waitcnt vmcnt(" #n ")" ::: "memory")
; #define PG8_WAIT_L(n) asm volatile("s_waitcnt lgkmcnt(" #n ")" ::: "memory")
; #define PG8_BAR __builtin_amdgcn_s_barrier()
; #define PG8_SCHED __builtin_amdgcn_sched_barrier(0)
; template <class Epi, class Sched, bool ALIGN_EPI = false, bool SP2 = false>
; __device__ __forceinline__ void gemm_phase(PG8_LAS unsigned char* lds, const Gemm g, const Sched& S, const Epi& E) {
;     ...
;             const bool last = (t == nt - 2);
;             const char* a1 = cA + (size_t)(t + 1) * kstep;
;             const char* a2 = last ? nA : cA + (size_t)(t + 2) * kstep; const char* b2 = last ? nB : cB + (size_t)(t + 2) * kstep;
;             const char* a3 = a2 + kstep; const char* b3 = b2 + kstep;
;             if (last && has_next) S.a_ready(nxt);
;             if constexpr (SP2) {
;             PG8_LDB(B0, 0, 0); PG8_LDB(B1, 0, 1); PG8_SCHED; PG8_LDA(At, 0, 0); PG8_STAGE(PG8_SA(1, 1), a1 + hstep, voffA);
;             PG8_WAIT_V(8); PG8_WAIT_L(0); PG8_BAR; PG8_MMA(0, 0, At, B0); PG8_MMA(0, 1, At, B1); PG8_BAR; PG8_SCHED;
;             PG8_LDA(At, 0, 1); PG8_STAGE(PG8_SB(0, 0), b2, voffB); PG8_STAGE(PG8_SB(0, 1), b2 + hstep, voffB); PG8_STAGE(PG8_SA(0, 0), a2, voffA);
.LBB0_190:
	s_add_u32 s18, s48, 0xfffc0080
	s_addc_u32 s19, s49, -1
	s_add_i32 s67, 0, 0x10000
	s_cmp_eq_u32 s66, 12
	s_cselect_b32 s53, s11, s19
	s_cselect_b32 s52, s35, s18
	s_cselect_b32 s51, s9, s65
	s_cselect_b32 s50, s38, s47
	s_add_i32 s18, 0, 0x14000
	v_add_u32_e32 v158, s67, v147
	v_add_u32_e32 v174, s18, v147
	ds_read_b128 v[142:145], v158
	ds_read_b128 v[150:153], v158 offset:1024
	ds_read_b128 v[154:157], v158 offset:2048
	ds_read_b128 v[158:161], v158 offset:3072
	ds_read_b128 v[162:165], v174
	ds_read_b128 v[166:169], v174 offset:1024
	ds_read_b128 v[170:173], v174 offset:2048
	ds_read_b128 v[174:177], v174 offset:3072
	v_lshl_add_u64 v[206:207], s[48:49], 0, v[138:139]
	s_add_i32 m0, s57, 0xc000
	ds_read_b128 v[178:181], v149
	ds_read_b128 v[182:185], v149 offset:1024
	ds_read_b128 v[186:189], v149 offset:2048
	ds_read_b128 v[190:193], v149 offset:3072
	ds_read_b128 v[194:197], v149 offset:4096
	ds_read_b128 v[198:201], v149 offset:5120
	ds_read_b128 v[202:205], v149 offset:6144
	ds_read_b128 v[212:215], v149 offset:7168
	global_load_lds_dwordx4 v[206:207], off
	v_lshl_add_u64 v[206:207], s[48:49], 0, v[140:141]
	s_add_i32 m0, s57, 0xe000
	s_nop 0
	global_load_lds_dwordx4 v[206:207], off
	s_waitcnt vmcnt(8)
	s_waitcnt lgkmcnt(0)
	s_setprio 1
	s_barrier
	v_mfma_f32_16x16x32_bf16 v[124:127], v[142:145], v[178:181], v[124:127]
	v_mfma_f32_16x16x32_bf16 v[120:123], v[154:157], v[178:181], v[120:123]
	v_mfma_f32_16x16x32_bf16 v[108:111], v[142:145], v[186:189], v[108:111]
	v_mfma_f32_16x16x32_bf16 v[104:107], v[154:157], v[186:189], v[104:107]
	v_mfma_f32_16x16x32_bf16 v[92:95], v[142:145], v[194:197], v[92:95]
	v_mfma_f32_16x16x32_bf16 v[88:91], v[154:157], v[194:197], v[88:91]
	v_mfma_f32_16x16x32_bf16 v[76:79], v[142:145], v[202:205], v[76:79]
	v_mfma_f32_16x16x32_bf16 v[72:75], v[154:157], v[202:205], v[72:75]
	v_mfma_f32_16x16x32_bf16 v[124:127], v[150:153], v[182:185], v[124:127]
	v_mfma_f32_16x16x32_bf16 v[120:123], v[158:161], v[182:185], v[120:123]
	v_mfma_f32_16x16x32_bf16 v[108:111], v[150:153], v[190:193], v[108:111]
	v_mfma_f32_16x16x32_bf16 v[104:107], v[158:161], v[190:193], v[104:107]
	v_mfma_f32_16x16x32_bf16 v[92:95], v[150:153], v[198:201], v[92:95]
	v_mfma_f32_16x16x32_bf16 v[88:91], v[158:161], v[198:201], v[88:91]
	v_mfma_f32_16x16x32_bf16 v[76:79], v[150:153], v[212:215], v[76:79]
	v_mfma_f32_16x16x32_bf16 v[72:75], v[158:161], v[212:215], v[72:75]
	v_mfma_f32_16x16x32_bf16 v[116:119], v[162:165], v[178:181], v[116:119]
	v_mfma_f32_16x16x32_bf16 v[112:115], v[170:173], v[178:181], v[112:115]
	v_mfma_f32_16x16x32_bf16 v[100:103], v[162:165], v[186:189], v[100:103]
	v_mfma_f32_16x16x32_bf16 v[96:99], v[170:173], v[186:189], v[96:99]
	v_mfma_f32_16x16x32_bf16 v[84:87], v[162:165], v[194:197], v[84:87]
	v_mfma_f32_16x16x32_bf16 v[80:83], v[170:173], v[194:197], v[80:83]
	v_mfma_f32_16x16x32_bf16 v[68:71], v[162:165], v[202:205], v[68:71]
	v_mfma_f32_16x16x32_bf16 v[64:67], v[170:173], v[202:205], v[64:67]
	v_mfma_f32_16x16x32_bf16 v[116:119], v[166:169], v[182:185], v[116:119]
	v_mfma_f32_16x16x32_bf16 v[112:115], v[174:177], v[182:185], v[112:115]
	v_mfma_f32_16x16x32_bf16 v[100:103], v[166:169], v[190:193], v[100:103]
	v_mfma_f32_16x16x32_bf16 v[96:99], v[174:177], v[190:193], v[96:99]
	v_mfma_f32_16x16x32_bf16 v[84:87], v[166:169], v[198:201], v[84:87]
	v_mfma_f32_16x16x32_bf16 v[80:83], v[174:177], v[198:201], v[80:83]
	v_mfma_f32_16x16x32_bf16 v[68:71], v[166:169], v[212:215], v[68:71]
	v_mfma_f32_16x16x32_bf16 v[64:67], v[174:177], v[212:215], v[64:67]
	s_barrier
	s_setprio 0
	s_add_i32 s19, s67, s56
	v_lshl_add_u64 v[206:207], s[50:51], 0, v[130:131]
	s_mov_b32 m0, s19
	ds_read_b128 v[178:181], v149 offset:16384
	ds_read_b128 v[182:185], v149 offset:17408
	ds_read_b128 v[186:189], v149 offset:18432
	ds_read_b128 v[190:193], v149 offset:19456
	ds_read_b128 v[194:197], v149 offset:20480
	ds_read_b128 v[198:201], v149 offset:21504
	ds_read_b128 v[202:205], v149 offset:22528
	ds_read_b128 v[212:215], v149 offset:23552
	global_load_lds_dwordx4 v[206:207], off
	s_add_i32 m0, s19, 0x2000
	s_add_u32 s68, s50, 0x40000
	v_lshl_add_u64 v[218:219], s[50:51], 0, v[134:135]
	s_addc_u32 s69, s51, 0
	s_add_i32 s18, s18, s56
	global_load_lds_dwordx4 v[218:219], off
	v_lshl_add_u64 v[220:221], s[68:69], 0, v[130:131]
	s_mov_b32 m0, s18
	v_lshl_add_u64 v[222:223], s[52:53], 0, v[132:133]
	global_load_lds_dwordx4 v[220:221], off
	v_lshl_add_u64 v[220:221], s[68:69], 0, v[134:135]
	s_add_i32 m0, s18, 0x2000
	s_nop 0
	global_load_lds_dwordx4 v[220:221], off
	v_lshl_add_u64 v[220:221], s[52:53], 0, v[128:129]
	s_mov_b32 m0, s57
	s_nop 0
	global_load_lds_dwordx4 v[220:221], off
	s_mov_b32 m0, s58
	s_nop 0
	global_load_lds_dwordx4 v[222:223], off
	s_waitcnt vmcnt(8)
	s_waitcnt lgkmcnt(0)
	s_setprio 1
	s_barrier
; #define PG8_STAGE(bufoff, gbase, voff) do { _Pragma("unroll") for (int _i = 0; _i < 2; ++_i) \
;         __builtin_amdgcn_global_load_lds((const unsigned*)((const char*)(gbase) + (voff)[_i]), (PG8_LAS unsigned*)(lds + (bufoff) + ldsw + _i * 8192), 16, 0, 0); } while (0)
; #define PG8_LDA(dst, b, h) do { _Pragma("unroll") for (int m = 0; m < 4; ++m) _Pragma("unroll") for (int k = 0; k < 2; ++k) dst[m][k] = *(const PG8_LAS bf16x8*)(lds + PG8_SA(b, h) + aoff + m * 2048 + k * 1024); } while (0)
; #define PG8_LDB(dst, b, h) do { _Pragma("unroll") for (int n = 0; n < 2; ++n) _Pragma("unroll") for (int k = 0; k < 2; ++k) dst[n][k] = *(const PG8_LAS bf16x8*)(lds + PG8_SB(b, h) + boff + n * 2048 + k * 1024); } while (0)
; #define PG8_MMA(ai, bj, At, Bt) do { __builtin_amdgcn_s_setprio(1); _Pragma("unroll") for (int m = 0; m < 4; ++m) _Pragma("unroll") for (int n = 0; n < 2; ++n) _Pragma("unroll") for (int k = 0; k < 2; ++k) \
;         acc[ai][bj][m][n] = __builtin_amdgcn_mfma_f32_16x16x32_bf16(Bt[n][k], At[m][k], acc[ai][bj][m][n], 0, 0, 0); __builtin_amdgcn_s_setprio(0); } while (0)
; #define PG8_WAIT_V(n) asm volatile("s_waitcnt vmcnt(" #n ")" ::: "memory")
; #define PG8_WAIT_L(n) asm volatile("s_waitcnt lgkmcnt(" #n ")" ::: "memory")
; #define PG8_BAR __builtin_amdgcn_s_barrier()
; #define PG8_SCHED __builtin_amdgcn_sched_barrier(0)
; template <class Epi, class Sched, bool ALIGN_EPI = false, bool SP2 = false>
; __device__ __forceinline__ void gemm_phase(PG8_LAS unsigned char* lds, const Gemm g, const Sched& S, const Epi& E) {
;     ...
;             PG8_WAIT_V(8); PG8_WAIT_L(0); PG8_BAR; PG8_MMA(1, 0, At, B0); PG8_MMA(1, 1, At, B1); PG8_BAR; PG8_SCHED;
;             PG8_LDB(B0, 1, 0); PG8_LDB(B1, 1, 1); PG8_SCHED; PG8_LDA(At, 1, 0); PG8_STAGE(PG8_SA(0, 1), a2 + hstep, voffA);
;             PG8_WAIT_V(8); PG8_WAIT_L(0); PG8_BAR; PG8_MMA(0, 0, At, B0); PG8_MMA(0, 1, At, B1); PG8_BAR; PG8_SCHED;
	v_mfma_f32_16x16x32_bf16 v[60:63], v[142:145], v[178:181], v[60:63]
	v_mfma_f32_16x16x32_bf16 v[56:59], v[154:157], v[178:181], v[56:59]
	v_mfma_f32_16x16x32_bf16 v[44:47], v[142:145], v[186:189], v[44:47]
	v_mfma_f32_16x16x32_bf16 v[40:43], v[154:157], v[186:189], v[40:43]
	v_mfma_f32_16x16x32_bf16 v[28:31], v[142:145], v[194:197], v[28:31]
	v_mfma_f32_16x16x32_bf16 v[24:27], v[154:157], v[194:197], v[24:27]
	v_mfma_f32_16x16x32_bf16 v[12:15], v[142:145], v[202:205], v[12:15]
	v_mfma_f32_16x16x32_bf16 v[8:11], v[154:157], v[202:205], v[8:11]
	v_mfma_f32_16x16x32_bf16 v[60:63], v[150:153], v[182:185], v[60:63]
	v_mfma_f32_16x16x32_bf16 v[56:59], v[158:161], v[182:185], v[56:59]
	v_mfma_f32_16x16x32_bf16 v[44:47], v[150:153], v[190:193], v[44:47]
	v_mfma_f32_16x16x32_bf16 v[40:43], v[158:161], v[190:193], v[40:43]
	v_mfma_f32_16x16x32_bf16 v[28:31], v[150:153], v[198:201], v[28:31]
	v_mfma_f32_16x16x32_bf16 v[24:27], v[158:161], v[198:201], v[24:27]
	v_mfma_f32_16x16x32_bf16 v[12:15], v[150:153], v[212:215], v[12:15]
	v_mfma_f32_16x16x32_bf16 v[8:11], v[158:161], v[212:215], v[8:11]
	v_mfma_f32_16x16x32_bf16 v[52:55], v[162:165], v[178:181], v[52:55]
	v_mfma_f32_16x16x32_bf16 v[48:51], v[170:173], v[178:181], v[48:51]
	v_mfma_f32_16x16x32_bf16 v[36:39], v[162:165], v[186:189], v[36:39]
	v_mfma_f32_16x16x32_bf16 v[32:35], v[170:173], v[186:189], v[32:35]
	v_mfma_f32_16x16x32_bf16 v[20:23], v[162:165], v[194:197], v[20:23]
	v_mfma_f32_16x16x32_bf16 v[16:19], v[170:173], v[194:197], v[16:19]
	v_mfma_f32_16x16x32_bf16 v[4:7], v[162:165], v[202:205], v[4:7]
	v_mfma_f32_16x16x32_bf16 v[0:3], v[170:173], v[202:205], v[0:3]
	v_mfma_f32_16x16x32_bf16 v[52:55], v[166:169], v[182:185], v[52:55]
	v_mfma_f32_16x16x32_bf16 v[48:51], v[174:177], v[182:185], v[48:51]
	v_mfma_f32_16x16x32_bf16 v[36:39], v[166:169], v[190:193], v[36:39]
	v_mfma_f32_16x16x32_bf16 v[32:35], v[174:177], v[190:193], v[32:35]
	v_mfma_f32_16x16x32_bf16 v[20:23], v[166:169], v[198:201], v[20:23]
	v_mfma_f32_16x16x32_bf16 v[16:19], v[174:177], v[198:201], v[16:19]
	v_mfma_f32_16x16x32_bf16 v[4:7], v[166:169], v[212:215], v[4:7]
	v_mfma_f32_16x16x32_bf16 v[0:3], v[174:177], v[212:215], v[0:3]
	s_barrier
	s_setprio 0
	s_add_i32 s18, 0, 0x18000
	s_add_i32 s19, 0, 0x1c000
	v_add_u32_e32 v158, s18, v147
	v_add_u32_e32 v174, s19, v147
	ds_read_b128 v[142:145], v158
	ds_read_b128 v[150:153], v158 offset:1024
	ds_read_b128 v[154:157], v158 offset:2048
	ds_read_b128 v[158:161], v158 offset:3072
	ds_read_b128 v[162:165], v174
	ds_read_b128 v[166:169], v174 offset:1024
	ds_read_b128 v[170:173], v174 offset:2048
	ds_read_b128 v[174:177], v174 offset:3072
	s_add_u32 s52, s52, 0x40000
	s_addc_u32 s53, s53, 0
	s_mov_b32 m0, s59
	v_lshl_add_u64 v[224:225], s[52:53], 0, v[128:129]
	ds_read_b128 v[178:181], v149 offset:32768
	ds_read_b128 v[182:185], v149 offset:33792
	ds_read_b128 v[186:189], v149 offset:34816
	ds_read_b128 v[190:193], v149 offset:35840
	ds_read_b128 v[194:197], v149 offset:36864
	ds_read_b128 v[198:201], v149 offset:37888
	ds_read_b128 v[202:205], v149 offset:38912
	ds_read_b128 v[212:215], v149 offset:39936
	global_load_lds_dwordx4 v[224:225], off
	v_lshl_add_u64 v[224:225], s[52:53], 0, v[132:133]
	s_mov_b32 m0, s60
	s_nop 0
	global_load_lds_dwordx4 v[224:225], off
	s_waitcnt vmcnt(8)
	s_waitcnt lgkmcnt(0)
	s_setprio 1
	s_barrier
	v_mfma_f32_16x16x32_bf16 v[124:127], v[142:145], v[178:181], v[124:127]
	v_mfma_f32_16x16x32_bf16 v[120:123], v[154:157], v[178:181], v[120:123]
	v_mfma_f32_16x16x32_bf16 v[108:111], v[142:145], v[186:189], v[108:111]
	v_mfma_f32_16x16x32_bf16 v[104:107], v[154:157], v[186:189], v[104:107]
	v_mfma_f32_16x16x32_bf16 v[92:95], v[142:145], v[194:197], v[92:95]
	v_mfma_f32_16x16x32_bf16 v[88:91], v[154:157], v[194:197], v[88:91]
	v_mfma_f32_16x16x32_bf16 v[76:79], v[142:145], v[202:205], v[76:79]
	v_mfma_f32_16x16x32_bf16 v[72:75], v[154:157], v[202:205], v[72:75]
	v_mfma_f32_16x16x32_bf16 v[124:127], v[150:153], v[182:185], v[124:127]
	v_mfma_f32_16x16x32_bf16 v[120:123], v[158:161], v[182:185], v[120:123]
	v_mfma_f32_16x16x32_bf16 v[108:111], v[150:153], v[190:193], v[108:111]
	v_mfma_f32_16x16x32_bf16 v[104:107], v[158:161], v[190:193], v[104:107]
	v_mfma_f32_16x16x32_bf16 v[92:95], v[150:153], v[198:201], v[92:95]
	v_mfma_f32_16x16x32_bf16 v[88:91], v[158:161], v[198:201], v[88:91]
	v_mfma_f32_16x16x32_bf16 v[76:79], v[150:153], v[212:215], v[76:79]
	v_mfma_f32_16x16x32_bf16 v[72:75], v[158:161], v[212:215], v[72:75]
	v_mfma_f32_16x16x32_bf16 v[116:119], v[162:165], v[178:181], v[116:119]
	v_mfma_f32_16x16x32_bf16 v[112:115], v[170:173], v[178:181], v[112:115]
	v_mfma_f32_16x16x32_bf16 v[100:103], v[162:165], v[186:189], v[100:103]
	v_mfma_f32_16x16x32_bf16 v[96:99], v[170:173], v[186:189], v[96:99]
	v_mfma_f32_16x16x32_bf16 v[84:87], v[162:165], v[194:197], v[84:87]
	v_mfma_f32_16x16x32_bf16 v[80:83], v[170:173], v[194:197], v[80:83]
	v_mfma_f32_16x16x32_bf16 v[68:71], v[162:165], v[202:205], v[68:71]
	v_mfma_f32_16x16x32_bf16 v[64:67], v[170:173], v[202:205], v[64:67]
	v_mfma_f32_16x16x32_bf16 v[116:119], v[166:169], v[182:185], v[116:119]
	v_mfma_f32_16x16x32_bf16 v[112:115], v[174:177], v[182:185], v[112:115]
	v_mfma_f32_16x16x32_bf16 v[100:103], v[166:169], v[190:193], v[100:103]
	v_mfma_f32_16x16x32_bf16 v[96:99], v[174:177], v[190:193], v[96:99]
	v_mfma_f32_16x16x32_bf16 v[84:87], v[166:169], v[198:201], v[84:87]
	v_mfma_f32_16x16x32_bf16 v[80:83], v[174:177], v[198:201], v[80:83]
	v_mfma_f32_16x16x32_bf16 v[68:71], v[166:169], v[212:215], v[68:71]
	v_mfma_f32_16x16x32_bf16 v[64:67], v[174:177], v[212:215], v[64:67]
	s_barrier
; #define PG8_STAGE(bufoff, gbase, voff) do { _Pragma("unroll") for (int _i = 0; _i < 2; ++_i) \
;         __builtin_amdgcn_global_load_lds((const unsigned*)((const char*)(gbase) + (voff)[_i]), (PG8_LAS unsigned*)(lds + (bufoff) + ldsw + _i * 8192), 16, 0, 0); } while (0)
; #define PG8_LDA(dst, b, h) do { _Pragma("unroll") for (int m = 0; m < 4; ++m) _Pragma("unroll") for (int k = 0; k < 2; ++k) dst[m][k] = *(const PG8_LAS bf16x8*)(lds + PG8_SA(b, h) + aoff + m * 2048 + k * 1024); } while (0)
; #define PG8_MMA(ai, bj, At, Bt) do { __builtin_amdgcn_s_setprio(1); _Pragma("unroll") for (int m = 0; m < 4; ++m) _Pragma("unroll") for (int n = 0; n < 2; ++n) _Pragma("unroll") for (int k = 0; k < 2; ++k) \
;         acc[ai][bj][m][n] = __builtin_amdgcn_mfma_f32_16x16x32_bf16(Bt[n][k], At[m][k], acc[ai][bj][m][n], 0, 0, 0); __builtin_amdgcn_s_setprio(0); } while (0)
; #define PG8_WAIT_V(n) asm volatile("s_waitcnt vmcnt(" #n ")" ::: "memory")
; #define PG8_WAIT_L(n) asm volatile("s_waitcnt lgkmcnt(" #n ")" ::: "memory")
; #define PG8_BAR __builtin_amdgcn_s_barrier()
; #define PG8_SCHED __builtin_amdgcn_sched_barrier(0)
; template <class Epi, class Sched, bool ALIGN_EPI = false, bool SP2 = false>
; __device__ __forceinline__ void gemm_phase(PG8_LAS unsigned char* lds, const Gemm g, const Sched& S, const Epi& E) {
;     ...
;             PG8_LDA(At, 1, 1); PG8_STAGE(PG8_SB(1, 0), b3, voffB); PG8_STAGE(PG8_SB(1, 1), b3 + hstep, voffB); PG8_STAGE(PG8_SA(1, 0), a3, voffA);
;             PG8_WAIT_V(8); PG8_WAIT_L(0); PG8_BAR; PG8_MMA(1, 0, At, B0); PG8_MMA(1, 1, At, B1); PG8_BAR; PG8_SCHED;
;     ...
;         if constexpr (ALIGN_EPI) { if (wr == 0) PG8_BAR; }
	s_setprio 0
	s_add_i32 s18, s18, s56
	v_lshl_add_u64 v[206:207], v[206:207], 0, s[24:25]
	s_mov_b32 m0, s18
	ds_read_b128 v[178:181], v149 offset:49152
	ds_read_b128 v[182:185], v149 offset:50176
	ds_read_b128 v[186:189], v149 offset:51200
	ds_read_b128 v[190:193], v149 offset:52224
	ds_read_b128 v[194:197], v149 offset:53248
	ds_read_b128 v[198:201], v149 offset:54272
	ds_read_b128 v[202:205], v149 offset:55296
	ds_read_b128 v[212:215], v149 offset:56320
	global_load_lds_dwordx4 v[206:207], off
	s_add_i32 m0, s18, 0x2000
	s_add_u32 s50, s50, 0x40080
	v_lshl_add_u64 v[206:207], v[218:219], 0, s[24:25]
	s_addc_u32 s51, s51, 0
	s_add_i32 s18, s19, s56
	global_load_lds_dwordx4 v[206:207], off
	v_lshl_add_u64 v[206:207], s[50:51], 0, v[130:131]
	s_mov_b32 m0, s18
	s_nop 0
	global_load_lds_dwordx4 v[206:207], off
	v_lshl_add_u64 v[206:207], s[50:51], 0, v[134:135]
	s_add_i32 m0, s18, 0x2000
	s_nop 0
	global_load_lds_dwordx4 v[206:207], off
	v_lshl_add_u64 v[206:207], v[220:221], 0, s[24:25]
	s_mov_b32 m0, s61
	s_nop 0
	global_load_lds_dwordx4 v[206:207], off
	v_lshl_add_u64 v[206:207], v[222:223], 0, s[24:25]
	s_mov_b32 m0, s62
	s_nop 0
	global_load_lds_dwordx4 v[206:207], off
	s_waitcnt vmcnt(8)
	s_waitcnt lgkmcnt(0)
	s_setprio 1
	s_barrier
	v_mfma_f32_16x16x32_bf16 v[60:63], v[142:145], v[178:181], v[60:63]
	v_mfma_f32_16x16x32_bf16 v[56:59], v[154:157], v[178:181], v[56:59]
	v_mfma_f32_16x16x32_bf16 v[44:47], v[142:145], v[186:189], v[44:47]
	v_mfma_f32_16x16x32_bf16 v[40:43], v[154:157], v[186:189], v[40:43]
	v_mfma_f32_16x16x32_bf16 v[28:31], v[142:145], v[194:197], v[28:31]
	v_mfma_f32_16x16x32_bf16 v[24:27], v[154:157], v[194:197], v[24:27]
	v_mfma_f32_16x16x32_bf16 v[12:15], v[142:145], v[202:205], v[12:15]
	v_mfma_f32_16x16x32_bf16 v[8:11], v[154:157], v[202:205], v[8:11]
	v_mfma_f32_16x16x32_bf16 v[60:63], v[150:153], v[182:185], v[60:63]
	v_mfma_f32_16x16x32_bf16 v[56:59], v[158:161], v[182:185], v[56:59]
	v_mfma_f32_16x16x32_bf16 v[44:47], v[150:153], v[190:193], v[44:47]
	v_mfma_f32_16x16x32_bf16 v[40:43], v[158:161], v[190:193], v[40:43]
	v_mfma_f32_16x16x32_bf16 v[28:31], v[150:153], v[198:201], v[28:31]
	v_mfma_f32_16x16x32_bf16 v[24:27], v[158:161], v[198:201], v[24:27]
	v_mfma_f32_16x16x32_bf16 v[12:15], v[150:153], v[212:215], v[12:15]
	v_mfma_f32_16x16x32_bf16 v[8:11], v[158:161], v[212:215], v[8:11]
	v_mfma_f32_16x16x32_bf16 v[52:55], v[162:165], v[178:181], v[52:55]
	v_mfma_f32_16x16x32_bf16 v[48:51], v[170:173], v[178:181], v[48:51]
	v_mfma_f32_16x16x32_bf16 v[36:39], v[162:165], v[186:189], v[36:39]
	v_mfma_f32_16x16x32_bf16 v[32:35], v[170:173], v[186:189], v[32:35]
	v_mfma_f32_16x16x32_bf16 v[20:23], v[162:165], v[194:197], v[20:23]
	v_mfma_f32_16x16x32_bf16 v[16:19], v[170:173], v[194:197], v[16:19]
	v_mfma_f32_16x16x32_bf16 v[4:7], v[162:165], v[202:205], v[4:7]
	v_mfma_f32_16x16x32_bf16 v[0:3], v[170:173], v[202:205], v[0:3]
	v_mfma_f32_16x16x32_bf16 v[52:55], v[166:169], v[182:185], v[52:55]
	v_mfma_f32_16x16x32_bf16 v[48:51], v[174:177], v[182:185], v[48:51]
	v_mfma_f32_16x16x32_bf16 v[36:39], v[166:169], v[190:193], v[36:39]
	v_mfma_f32_16x16x32_bf16 v[32:35], v[174:177], v[190:193], v[32:35]
	v_mfma_f32_16x16x32_bf16 v[20:23], v[166:169], v[198:201], v[20:23]
	v_mfma_f32_16x16x32_bf16 v[16:19], v[174:177], v[198:201], v[16:19]
	v_mfma_f32_16x16x32_bf16 v[4:7], v[166:169], v[212:215], v[4:7]
	v_mfma_f32_16x16x32_bf16 v[0:3], v[174:177], v[212:215], v[0:3]
	s_barrier
	s_setprio 0
	s_add_i32 s66, s66, 2
	s_add_u32 s48, s48, 0x100
	s_addc_u32 s49, s49, 0
	s_add_u32 s47, s47, 0x100
	s_addc_u32 s65, s65, 0
	s_cmp_gt_u32 s66, 13
	s_cbranch_scc0 .LBB0_190
	s_and_b64 vcc, exec, s[6:7]
	s_cbranch_vccz .LBB0_193
	s_barrier

; #define PG8_STAGE(bufoff, gbase, voff) do { _Pragma("unroll") for (int _i = 0; _i < 2; ++_i) \
;         __builtin_amdgcn_global_load_lds((const unsigned*)((const char*)(gbase) + (voff)[_i]), (PG8_LAS unsigned*)(lds + (bufoff) + ldsw + _i * 8192), 16, 0, 0); } while (0)
; #define PG8_LDA(dst, b, h) do { _Pragma("unroll") for (int m = 0; m < 4; ++m) _Pragma("unroll") for (int k = 0; k < 2; ++k) dst[m][k] = *(const PG8_LAS bf16x8*)(lds + PG8_SA(b, h) + aoff + m * 2048 + k * 1024); } while (0)
; #define PG8_LDB(dst, b, h) do { _Pragma("unroll") for (int n = 0; n < 2; ++n) _Pragma("unroll") for (int k = 0; k < 2; ++k) dst[n][k] = *(const PG8_LAS bf16x8*)(lds + PG8_SB(b, h) + boff + n * 2048 + k * 1024); } while (0)
; #define PG8_MMA(ai, bj, At, Bt) do { __builtin_amdgcn_s_setprio(1); _Pragma("unroll") for (int m = 0; m < 4; ++m) _Pragma("unroll") for (int n = 0; n < 2; ++n) _Pragma("unroll") for (int k = 0; k < 2; ++k) \
;         acc[ai][bj][m][n] = __builtin_amdgcn_mfma_f32_16x16x32_bf16(Bt[n][k], At[m][k], acc[ai][bj][m][n], 0, 0, 0); __builtin_amdgcn_s_setprio(0); } while (0)
; #define PG8_WAIT_V(n) asm volatile("s_waitcnt vmcnt(" #n ")" ::: "memory")
; #define PG8_WAIT_L(n) asm volatile("s_waitcnt lgkmcnt(" #n ")" ::: "memory")
; #define PG8_BAR __builtin_amdgcn_s_barrier()
; #define PG8_SCHED __builtin_amdgcn_sched_barrier(0)
; template <class Epi, class Sched, bool ALIGN_EPI = false, bool SP2 = false>
; __device__ __forceinline__ void gemm_phase(PG8_LAS unsigned char* lds, const Gemm g, const Sched& S, const Epi& E) {
;     ...
;             const bool last = (t == nt - 2);
;             const char* a1 = cA + (size_t)(t + 1) * kstep;
;             const char* a2 = last ? nA : cA + (size_t)(t + 2) * kstep; const char* b2 = last ? nB : cB + (size_t)(t + 2) * kstep;
;             const char* a3 = a2 + kstep; const char* b3 = b2 + kstep;
;             if (last && has_next) S.a_ready(nxt);
;             if constexpr (SP2) {
;             PG8_LDB(B0, 0, 0); PG8_LDB(B1, 0, 1); PG8_SCHED; PG8_LDA(At, 0, 0); PG8_STAGE(PG8_SA(1, 1), a1 + hstep, voffA);
;             PG8_WAIT_V(8); PG8_WAIT_L(0); PG8_BAR; PG8_MMA(0, 0, At, B0); PG8_MMA(0, 1, At, B1); PG8_BAR; PG8_SCHED;
;             PG8_LDA(At, 0, 1); PG8_STAGE(PG8_SB(0, 0), b2, voffB); PG8_STAGE(PG8_SB(0, 1), b2 + hstep, voffB); PG8_STAGE(PG8_SA(0, 0), a2, voffA);
.LBB0_288:
	s_add_u32 s6, s4, 0xfffc0080
	s_addc_u32 s7, s5, -1
	s_add_i32 s18, 0, 0x10000
	s_cmp_eq_u32 vcc_lo, 12
	s_cselect_b32 s77, s73, s7
	s_cselect_b32 s76, s72, s6
	s_cselect_b32 s7, s9, s79
	s_cselect_b32 s6, s71, s78
	s_add_i32 vcc_hi, 0, 0x14000
	v_add_u32_e32 v76, s18, v196
	v_add_u32_e32 v100, vcc_hi, v196
	ds_read_b128 v[64:67], v76
	ds_read_b128 v[68:71], v76 offset:1024
	ds_read_b128 v[72:75], v76 offset:2048
	ds_read_b128 v[76:79], v76 offset:3072
	ds_read_b128 v[88:91], v100
	ds_read_b128 v[92:95], v100 offset:1024
	ds_read_b128 v[96:99], v100 offset:2048
	ds_read_b128 v[100:103], v100 offset:3072
	v_lshl_add_u64 v[164:165], s[4:5], 0, v[178:179]
	s_add_i32 m0, s91, 0xc000
	ds_read_b128 v[160:163], v218
	ds_read_b128 v[182:185], v218 offset:1024
	ds_read_b128 v[186:189], v218 offset:2048
	ds_read_b128 v[190:193], v218 offset:3072
	ds_read_b128 v[212:215], v218 offset:4096
	ds_read_b128 v[220:223], v218 offset:5120
	ds_read_b128 v[224:227], v218 offset:6144
	ds_read_b128 v[228:231], v218 offset:7168
	global_load_lds_dwordx4 v[164:165], off
	v_lshl_add_u64 v[164:165], s[4:5], 0, v[180:181]
	s_add_i32 m0, s91, 0xe000
	s_nop 0
	global_load_lds_dwordx4 v[164:165], off
	s_waitcnt vmcnt(8)
	s_waitcnt lgkmcnt(0)
	s_setprio 1
	s_barrier
	v_mfma_f32_16x16x32_bf16 v[156:159], v[64:67], v[160:163], v[156:159]
	v_mfma_f32_16x16x32_bf16 v[152:155], v[72:75], v[160:163], v[152:155]
	v_mfma_f32_16x16x32_bf16 v[140:143], v[64:67], v[186:189], v[140:143]
	v_mfma_f32_16x16x32_bf16 v[136:139], v[72:75], v[186:189], v[136:139]
	v_mfma_f32_16x16x32_bf16 v[124:127], v[64:67], v[212:215], v[124:127]
	v_mfma_f32_16x16x32_bf16 v[120:123], v[72:75], v[212:215], v[120:123]
	v_mfma_f32_16x16x32_bf16 v[108:111], v[64:67], v[224:227], v[108:111]
	v_mfma_f32_16x16x32_bf16 v[104:107], v[72:75], v[224:227], v[104:107]
	v_mfma_f32_16x16x32_bf16 v[156:159], v[68:71], v[182:185], v[156:159]
	v_mfma_f32_16x16x32_bf16 v[152:155], v[76:79], v[182:185], v[152:155]
	v_mfma_f32_16x16x32_bf16 v[140:143], v[68:71], v[190:193], v[140:143]
	v_mfma_f32_16x16x32_bf16 v[136:139], v[76:79], v[190:193], v[136:139]
	v_mfma_f32_16x16x32_bf16 v[124:127], v[68:71], v[220:223], v[124:127]
	v_mfma_f32_16x16x32_bf16 v[120:123], v[76:79], v[220:223], v[120:123]
	v_mfma_f32_16x16x32_bf16 v[108:111], v[68:71], v[228:231], v[108:111]
	v_mfma_f32_16x16x32_bf16 v[104:107], v[76:79], v[228:231], v[104:107]
	v_mfma_f32_16x16x32_bf16 v[148:151], v[88:91], v[160:163], v[148:151]
	v_mfma_f32_16x16x32_bf16 v[144:147], v[96:99], v[160:163], v[144:147]
	v_mfma_f32_16x16x32_bf16 v[132:135], v[88:91], v[186:189], v[132:135]
	v_mfma_f32_16x16x32_bf16 v[128:131], v[96:99], v[186:189], v[128:131]
	v_mfma_f32_16x16x32_bf16 v[116:119], v[88:91], v[212:215], v[116:119]
	v_mfma_f32_16x16x32_bf16 v[112:115], v[96:99], v[212:215], v[112:115]
	v_mfma_f32_16x16x32_bf16 v[84:87], v[88:91], v[224:227], v[84:87]
	v_mfma_f32_16x16x32_bf16 v[80:83], v[96:99], v[224:227], v[80:83]
	v_mfma_f32_16x16x32_bf16 v[148:151], v[92:95], v[182:185], v[148:151]
	v_mfma_f32_16x16x32_bf16 v[144:147], v[100:103], v[182:185], v[144:147]
	v_mfma_f32_16x16x32_bf16 v[132:135], v[92:95], v[190:193], v[132:135]
	v_mfma_f32_16x16x32_bf16 v[128:131], v[100:103], v[190:193], v[128:131]
	v_mfma_f32_16x16x32_bf16 v[116:119], v[92:95], v[220:223], v[116:119]
	v_mfma_f32_16x16x32_bf16 v[112:115], v[100:103], v[220:223], v[112:115]
	v_mfma_f32_16x16x32_bf16 v[84:87], v[92:95], v[228:231], v[84:87]
	v_mfma_f32_16x16x32_bf16 v[80:83], v[100:103], v[228:231], v[80:83]
	s_barrier
	s_setprio 0
	s_add_i32 s18, s18, s85
	v_lshl_add_u64 v[164:165], s[6:7], 0, v[208:209]
	s_mov_b32 m0, s18
	ds_read_b128 v[160:163], v218 offset:16384
	ds_read_b128 v[182:185], v218 offset:17408
	ds_read_b128 v[186:189], v218 offset:18432
	ds_read_b128 v[190:193], v218 offset:19456
	ds_read_b128 v[212:215], v218 offset:20480
	ds_read_b128 v[220:223], v218 offset:21504
	ds_read_b128 v[224:227], v218 offset:22528
	ds_read_b128 v[228:231], v218 offset:23552
	global_load_lds_dwordx4 v[164:165], off
	s_add_i32 m0, s18, 0x2000
	s_add_u32 s18, s6, 0x40000
	v_lshl_add_u64 v[194:195], s[6:7], 0, v[170:171]
	s_addc_u32 s19, s7, 0
	s_add_i32 vcc_hi, vcc_hi, s85
	global_load_lds_dwordx4 v[194:195], off
	v_lshl_add_u64 v[232:233], s[18:19], 0, v[208:209]
	s_mov_b32 m0, vcc_hi
	v_lshl_add_u64 v[234:235], s[76:77], 0, v[168:169]
	global_load_lds_dwordx4 v[232:233], off
	v_lshl_add_u64 v[232:233], s[18:19], 0, v[170:171]
	s_add_i32 m0, vcc_hi, 0x2000
	s_nop 0
	global_load_lds_dwordx4 v[232:233], off
	v_lshl_add_u64 v[232:233], s[76:77], 0, v[166:167]
	s_mov_b32 m0, s91
	s_nop 0
	global_load_lds_dwordx4 v[232:233], off
	s_mov_b32 m0, s92
	s_nop 0
	global_load_lds_dwordx4 v[234:235], off
	s_waitcnt vmcnt(8)
	s_waitcnt lgkmcnt(0)
	s_setprio 1
	s_barrier
; #define PG8_STAGE(bufoff, gbase, voff) do { _Pragma("unroll") for (int _i = 0; _i < 2; ++_i) \
;         __builtin_amdgcn_global_load_lds((const unsigned*)((const char*)(gbase) + (voff)[_i]), (PG8_LAS unsigned*)(lds + (bufoff) + ldsw + _i * 8192), 16, 0, 0); } while (0)
; #define PG8_LDA(dst, b, h) do { _Pragma("unroll") for (int m = 0; m < 4; ++m) _Pragma("unroll") for (int k = 0; k < 2; ++k) dst[m][k] = *(const PG8_LAS bf16x8*)(lds + PG8_SA(b, h) + aoff + m * 2048 + k * 1024); } while (0)
; #define PG8_LDB(dst, b, h) do { _Pragma("unroll") for (int n = 0; n < 2; ++n) _Pragma("unroll") for (int k = 0; k < 2; ++k) dst[n][k] = *(const PG8_LAS bf16x8*)(lds + PG8_SB(b, h) + boff + n * 2048 + k * 1024); } while (0)
; #define PG8_MMA(ai, bj, At, Bt) do { __builtin_amdgcn_s_setprio(1); _Pragma("unroll") for (int m = 0; m < 4; ++m) _Pragma("unroll") for (int n = 0; n < 2; ++n) _Pragma("unroll") for (int k = 0; k < 2; ++k) \
;         acc[ai][bj][m][n] = __builtin_amdgcn_mfma_f32_16x16x32_bf16(Bt[n][k], At[m][k], acc[ai][bj][m][n], 0, 0, 0); __builtin_amdgcn_s_setprio(0); } while (0)
; #define PG8_WAIT_V(n) asm volatile("s_waitcnt vmcnt(" #n ")" ::: "memory")
; #define PG8_WAIT_L(n) asm volatile("s_waitcnt lgkmcnt(" #n ")" ::: "memory")
; #define PG8_BAR __builtin_amdgcn_s_barrier()
; #define PG8_SCHED __builtin_amdgcn_sched_barrier(0)
; template <class Epi, class Sched, bool ALIGN_EPI = false, bool SP2 = false>
; __device__ __forceinline__ void gemm_phase(PG8_LAS unsigned char* lds, const Gemm g, const Sched& S, const Epi& E) {
;     ...
;             PG8_WAIT_V(8); PG8_WAIT_L(0); PG8_BAR; PG8_MMA(1, 0, At, B0); PG8_MMA(1, 1, At, B1); PG8_BAR; PG8_SCHED;
;             PG8_LDB(B0, 1, 0); PG8_LDB(B1, 1, 1); PG8_SCHED; PG8_LDA(At, 1, 0); PG8_STAGE(PG8_SA(0, 1), a2 + hstep, voffA);
;             PG8_WAIT_V(8); PG8_WAIT_L(0); PG8_BAR; PG8_MMA(0, 0, At, B0); PG8_MMA(0, 1, At, B1); PG8_BAR; PG8_SCHED;
	v_mfma_f32_16x16x32_bf16 v[60:63], v[64:67], v[160:163], v[60:63]
	v_mfma_f32_16x16x32_bf16 v[56:59], v[72:75], v[160:163], v[56:59]
	v_mfma_f32_16x16x32_bf16 v[44:47], v[64:67], v[186:189], v[44:47]
	v_mfma_f32_16x16x32_bf16 v[40:43], v[72:75], v[186:189], v[40:43]
	v_mfma_f32_16x16x32_bf16 v[28:31], v[64:67], v[212:215], v[28:31]
	v_mfma_f32_16x16x32_bf16 v[24:27], v[72:75], v[212:215], v[24:27]
	v_mfma_f32_16x16x32_bf16 v[12:15], v[64:67], v[224:227], v[12:15]
	v_mfma_f32_16x16x32_bf16 v[8:11], v[72:75], v[224:227], v[8:11]
	v_mfma_f32_16x16x32_bf16 v[60:63], v[68:71], v[182:185], v[60:63]
	v_mfma_f32_16x16x32_bf16 v[56:59], v[76:79], v[182:185], v[56:59]
	v_mfma_f32_16x16x32_bf16 v[44:47], v[68:71], v[190:193], v[44:47]
	v_mfma_f32_16x16x32_bf16 v[40:43], v[76:79], v[190:193], v[40:43]
	v_mfma_f32_16x16x32_bf16 v[28:31], v[68:71], v[220:223], v[28:31]
	v_mfma_f32_16x16x32_bf16 v[24:27], v[76:79], v[220:223], v[24:27]
	v_mfma_f32_16x16x32_bf16 v[12:15], v[68:71], v[228:231], v[12:15]
	v_mfma_f32_16x16x32_bf16 v[8:11], v[76:79], v[228:231], v[8:11]
	v_mfma_f32_16x16x32_bf16 v[52:55], v[88:91], v[160:163], v[52:55]
	v_mfma_f32_16x16x32_bf16 v[48:51], v[96:99], v[160:163], v[48:51]
	v_mfma_f32_16x16x32_bf16 v[36:39], v[88:91], v[186:189], v[36:39]
	v_mfma_f32_16x16x32_bf16 v[32:35], v[96:99], v[186:189], v[32:35]
	v_mfma_f32_16x16x32_bf16 v[20:23], v[88:91], v[212:215], v[20:23]
	v_mfma_f32_16x16x32_bf16 v[16:19], v[96:99], v[212:215], v[16:19]
	v_mfma_f32_16x16x32_bf16 v[4:7], v[88:91], v[224:227], v[4:7]
	v_mfma_f32_16x16x32_bf16 v[0:3], v[96:99], v[224:227], v[0:3]
	v_mfma_f32_16x16x32_bf16 v[52:55], v[92:95], v[182:185], v[52:55]
	v_mfma_f32_16x16x32_bf16 v[48:51], v[100:103], v[182:185], v[48:51]
	v_mfma_f32_16x16x32_bf16 v[36:39], v[92:95], v[190:193], v[36:39]
	v_mfma_f32_16x16x32_bf16 v[32:35], v[100:103], v[190:193], v[32:35]
	v_mfma_f32_16x16x32_bf16 v[20:23], v[92:95], v[220:223], v[20:23]
	v_mfma_f32_16x16x32_bf16 v[16:19], v[100:103], v[220:223], v[16:19]
	v_mfma_f32_16x16x32_bf16 v[4:7], v[92:95], v[228:231], v[4:7]
	v_mfma_f32_16x16x32_bf16 v[0:3], v[100:103], v[228:231], v[0:3]
	s_barrier
	s_setprio 0
	s_add_i32 vcc_hi, 0, 0x18000
	s_add_i32 s34, 0, 0x1c000
	v_add_u32_e32 v76, vcc_hi, v196
	v_add_u32_e32 v100, s34, v196
	ds_read_b128 v[64:67], v76
	ds_read_b128 v[68:71], v76 offset:1024
	ds_read_b128 v[72:75], v76 offset:2048
	ds_read_b128 v[76:79], v76 offset:3072
	ds_read_b128 v[88:91], v100
	ds_read_b128 v[92:95], v100 offset:1024
	ds_read_b128 v[96:99], v100 offset:2048
	ds_read_b128 v[100:103], v100 offset:3072
	s_add_u32 s18, s76, 0x40000
	s_addc_u32 s19, s77, 0
	s_mov_b32 m0, s93
	v_lshl_add_u64 v[236:237], s[18:19], 0, v[166:167]
	ds_read_b128 v[160:163], v218 offset:32768
	ds_read_b128 v[182:185], v218 offset:33792
	ds_read_b128 v[186:189], v218 offset:34816
	ds_read_b128 v[190:193], v218 offset:35840
	ds_read_b128 v[212:215], v218 offset:36864
	ds_read_b128 v[220:223], v218 offset:37888
	ds_read_b128 v[224:227], v218 offset:38912
	ds_read_b128 v[228:231], v218 offset:39936
	global_load_lds_dwordx4 v[236:237], off
	v_lshl_add_u64 v[236:237], s[18:19], 0, v[168:169]
	s_mov_b32 m0, s94
	s_nop 0
	global_load_lds_dwordx4 v[236:237], off
	s_waitcnt vmcnt(8)
	s_waitcnt lgkmcnt(0)
	s_setprio 1
	s_barrier
	v_mfma_f32_16x16x32_bf16 v[156:159], v[64:67], v[160:163], v[156:159]
	v_mfma_f32_16x16x32_bf16 v[152:155], v[72:75], v[160:163], v[152:155]
	v_mfma_f32_16x16x32_bf16 v[140:143], v[64:67], v[186:189], v[140:143]
	v_mfma_f32_16x16x32_bf16 v[136:139], v[72:75], v[186:189], v[136:139]
	v_mfma_f32_16x16x32_bf16 v[124:127], v[64:67], v[212:215], v[124:127]
	v_mfma_f32_16x16x32_bf16 v[120:123], v[72:75], v[212:215], v[120:123]
	v_mfma_f32_16x16x32_bf16 v[108:111], v[64:67], v[224:227], v[108:111]
	v_mfma_f32_16x16x32_bf16 v[104:107], v[72:75], v[224:227], v[104:107]
	v_mfma_f32_16x16x32_bf16 v[156:159], v[68:71], v[182:185], v[156:159]
	v_mfma_f32_16x16x32_bf16 v[152:155], v[76:79], v[182:185], v[152:155]
	v_mfma_f32_16x16x32_bf16 v[140:143], v[68:71], v[190:193], v[140:143]
	v_mfma_f32_16x16x32_bf16 v[136:139], v[76:79], v[190:193], v[136:139]
	v_mfma_f32_16x16x32_bf16 v[124:127], v[68:71], v[220:223], v[124:127]
	v_mfma_f32_16x16x32_bf16 v[120:123], v[76:79], v[220:223], v[120:123]
	v_mfma_f32_16x16x32_bf16 v[108:111], v[68:71], v[228:231], v[108:111]
	v_mfma_f32_16x16x32_bf16 v[104:107], v[76:79], v[228:231], v[104:107]
	v_mfma_f32_16x16x32_bf16 v[148:151], v[88:91], v[160:163], v[148:151]
	v_mfma_f32_16x16x32_bf16 v[144:147], v[96:99], v[160:163], v[144:147]
	v_mfma_f32_16x16x32_bf16 v[132:135], v[88:91], v[186:189], v[132:135]
	v_mfma_f32_16x16x32_bf16 v[128:131], v[96:99], v[186:189], v[128:131]
	v_mfma_f32_16x16x32_bf16 v[116:119], v[88:91], v[212:215], v[116:119]
	v_mfma_f32_16x16x32_bf16 v[112:115], v[96:99], v[212:215], v[112:115]
	v_mfma_f32_16x16x32_bf16 v[84:87], v[88:91], v[224:227], v[84:87]
	v_mfma_f32_16x16x32_bf16 v[80:83], v[96:99], v[224:227], v[80:83]
	v_mfma_f32_16x16x32_bf16 v[148:151], v[92:95], v[182:185], v[148:151]
	v_mfma_f32_16x16x32_bf16 v[144:147], v[100:103], v[182:185], v[144:147]
	v_mfma_f32_16x16x32_bf16 v[132:135], v[92:95], v[190:193], v[132:135]
	v_mfma_f32_16x16x32_bf16 v[128:131], v[100:103], v[190:193], v[128:131]
	v_mfma_f32_16x16x32_bf16 v[116:119], v[92:95], v[220:223], v[116:119]
	v_mfma_f32_16x16x32_bf16 v[112:115], v[100:103], v[220:223], v[112:115]
	v_mfma_f32_16x16x32_bf16 v[84:87], v[92:95], v[228:231], v[84:87]
	v_mfma_f32_16x16x32_bf16 v[80:83], v[100:103], v[228:231], v[80:83]
	s_barrier
; #define PG8_STAGE(bufoff, gbase, voff) do { _Pragma("unroll") for (int _i = 0; _i < 2; ++_i) \
;         __builtin_amdgcn_global_load_lds((const unsigned*)((const char*)(gbase) + (voff)[_i]), (PG8_LAS unsigned*)(lds + (bufoff) + ldsw + _i * 8192), 16, 0, 0); } while (0)
; #define PG8_LDA(dst, b, h) do { _Pragma("unroll") for (int m = 0; m < 4; ++m) _Pragma("unroll") for (int k = 0; k < 2; ++k) dst[m][k] = *(const PG8_LAS bf16x8*)(lds + PG8_SA(b, h) + aoff + m * 2048 + k * 1024); } while (0)
; #define PG8_MMA(ai, bj, At, Bt) do { __builtin_amdgcn_s_setprio(1); _Pragma("unroll") for (int m = 0; m < 4; ++m) _Pragma("unroll") for (int n = 0; n < 2; ++n) _Pragma("unroll") for (int k = 0; k < 2; ++k) \
;         acc[ai][bj][m][n] = __builtin_amdgcn_mfma_f32_16x16x32_bf16(Bt[n][k], At[m][k], acc[ai][bj][m][n], 0, 0, 0); __builtin_amdgcn_s_setprio(0); } while (0)
; #define PG8_WAIT_V(n) asm volatile("s_waitcnt vmcnt(" #n ")" ::: "memory")
; #define PG8_WAIT_L(n) asm volatile("s_waitcnt lgkmcnt(" #n ")" ::: "memory")
; #define PG8_BAR __builtin_amdgcn_s_barrier()
; #define PG8_SCHED __builtin_amdgcn_sched_barrier(0)
; template <class Epi, class Sched, bool ALIGN_EPI = false, bool SP2 = false>
; __device__ __forceinline__ void gemm_phase(PG8_LAS unsigned char* lds, const Gemm g, const Sched& S, const Epi& E) {
;     ...
;             PG8_LDA(At, 1, 1); PG8_STAGE(PG8_SB(1, 0), b3, voffB); PG8_STAGE(PG8_SB(1, 1), b3 + hstep, voffB); PG8_STAGE(PG8_SA(1, 0), a3, voffA);
;             PG8_WAIT_V(8); PG8_WAIT_L(0); PG8_BAR; PG8_MMA(1, 0, At, B0); PG8_MMA(1, 1, At, B1); PG8_BAR; PG8_SCHED;
;     ...
;         if constexpr (ALIGN_EPI) { if (wr == 0) PG8_BAR; }
	s_setprio 0
	s_add_i32 s18, vcc_hi, s85
	v_lshl_add_u64 v[164:165], v[164:165], 0, s[24:25]
	s_mov_b32 m0, s18
	ds_read_b128 v[160:163], v218 offset:49152
	ds_read_b128 v[182:185], v218 offset:50176
	ds_read_b128 v[186:189], v218 offset:51200
	ds_read_b128 v[190:193], v218 offset:52224
	ds_read_b128 v[212:215], v218 offset:53248
	ds_read_b128 v[220:223], v218 offset:54272
	ds_read_b128 v[224:227], v218 offset:55296
	ds_read_b128 v[228:231], v218 offset:56320
	global_load_lds_dwordx4 v[164:165], off
	s_add_i32 m0, s18, 0x2000
	s_add_u32 s6, s6, 0x40080
	v_lshl_add_u64 v[164:165], v[194:195], 0, s[24:25]
	s_addc_u32 s7, s7, 0
	s_add_i32 s18, s34, s85
	global_load_lds_dwordx4 v[164:165], off
	v_lshl_add_u64 v[164:165], s[6:7], 0, v[208:209]
	s_mov_b32 m0, s18
	s_nop 0
	global_load_lds_dwordx4 v[164:165], off
	v_lshl_add_u64 v[164:165], s[6:7], 0, v[170:171]
	s_add_i32 m0, s18, 0x2000
	s_nop 0
	global_load_lds_dwordx4 v[164:165], off
	v_lshl_add_u64 v[164:165], v[232:233], 0, s[24:25]
	s_mov_b32 m0, s95
	s_nop 0
	global_load_lds_dwordx4 v[164:165], off
	v_lshl_add_u64 v[164:165], v[234:235], 0, s[24:25]
	s_mov_b32 m0, s96
	s_nop 0
	global_load_lds_dwordx4 v[164:165], off
	s_waitcnt vmcnt(8)
	s_waitcnt lgkmcnt(0)
	s_setprio 1
	s_barrier
	v_mfma_f32_16x16x32_bf16 v[60:63], v[64:67], v[160:163], v[60:63]
	v_mfma_f32_16x16x32_bf16 v[56:59], v[72:75], v[160:163], v[56:59]
	v_mfma_f32_16x16x32_bf16 v[44:47], v[64:67], v[186:189], v[44:47]
	v_mfma_f32_16x16x32_bf16 v[40:43], v[72:75], v[186:189], v[40:43]
	v_mfma_f32_16x16x32_bf16 v[28:31], v[64:67], v[212:215], v[28:31]
	v_mfma_f32_16x16x32_bf16 v[24:27], v[72:75], v[212:215], v[24:27]
	v_mfma_f32_16x16x32_bf16 v[12:15], v[64:67], v[224:227], v[12:15]
	v_mfma_f32_16x16x32_bf16 v[8:11], v[72:75], v[224:227], v[8:11]
	v_mfma_f32_16x16x32_bf16 v[60:63], v[68:71], v[182:185], v[60:63]
	v_mfma_f32_16x16x32_bf16 v[56:59], v[76:79], v[182:185], v[56:59]
	v_mfma_f32_16x16x32_bf16 v[44:47], v[68:71], v[190:193], v[44:47]
	v_mfma_f32_16x16x32_bf16 v[40:43], v[76:79], v[190:193], v[40:43]
	v_mfma_f32_16x16x32_bf16 v[28:31], v[68:71], v[220:223], v[28:31]
	v_mfma_f32_16x16x32_bf16 v[24:27], v[76:79], v[220:223], v[24:27]
	v_mfma_f32_16x16x32_bf16 v[12:15], v[68:71], v[228:231], v[12:15]
	v_mfma_f32_16x16x32_bf16 v[8:11], v[76:79], v[228:231], v[8:11]
	v_mfma_f32_16x16x32_bf16 v[52:55], v[88:91], v[160:163], v[52:55]
	v_mfma_f32_16x16x32_bf16 v[48:51], v[96:99], v[160:163], v[48:51]
	v_mfma_f32_16x16x32_bf16 v[36:39], v[88:91], v[186:189], v[36:39]
	v_mfma_f32_16x16x32_bf16 v[32:35], v[96:99], v[186:189], v[32:35]
	v_mfma_f32_16x16x32_bf16 v[20:23], v[88:91], v[212:215], v[20:23]
	v_mfma_f32_16x16x32_bf16 v[16:19], v[96:99], v[212:215], v[16:19]
	v_mfma_f32_16x16x32_bf16 v[4:7], v[88:91], v[224:227], v[4:7]
	v_mfma_f32_16x16x32_bf16 v[0:3], v[96:99], v[224:227], v[0:3]
	v_mfma_f32_16x16x32_bf16 v[52:55], v[92:95], v[182:185], v[52:55]
	v_mfma_f32_16x16x32_bf16 v[48:51], v[100:103], v[182:185], v[48:51]
	v_mfma_f32_16x16x32_bf16 v[36:39], v[92:95], v[190:193], v[36:39]
	v_mfma_f32_16x16x32_bf16 v[32:35], v[100:103], v[190:193], v[32:35]
	v_mfma_f32_16x16x32_bf16 v[20:23], v[92:95], v[220:223], v[20:23]
	v_mfma_f32_16x16x32_bf16 v[16:19], v[100:103], v[220:223], v[16:19]
	v_mfma_f32_16x16x32_bf16 v[4:7], v[92:95], v[228:231], v[4:7]
	v_mfma_f32_16x16x32_bf16 v[0:3], v[100:103], v[228:231], v[0:3]
	s_barrier
	s_setprio 0
	s_add_i32 vcc_lo, vcc_lo, 2
	s_add_u32 s4, s4, 0x100
	s_addc_u32 s5, s5, 0
	s_add_u32 s78, s78, 0x100
	s_addc_u32 s79, s79, 0
	s_cmp_gt_u32 vcc_lo, 13
	s_cbranch_scc0 .LBB0_288
	s_and_b64 vcc, exec, s[58:59]
	s_cbranch_vccz .LBB0_291
	s_barrier

; #define PG8_STAGE(bufoff, gbase, voff) do { _Pragma("unroll") for (int _i = 0; _i < 2; ++_i) \
;         __builtin_amdgcn_global_load_lds((const unsigned*)((const char*)(gbase) + (voff)[_i]), (PG8_LAS unsigned*)(lds + (bufoff) + ldsw + _i * 8192), 16, 0, 0); } while (0)
; #define PG8_LDA(dst, b, h) do { _Pragma("unroll") for (int m = 0; m < 4; ++m) _Pragma("unroll") for (int k = 0; k < 2; ++k) dst[m][k] = *(const PG8_LAS bf16x8*)(lds + PG8_SA(b, h) + aoff + m * 2048 + k * 1024); } while (0)
; #define PG8_LDB(dst, b, h) do { _Pragma("unroll") for (int n = 0; n < 2; ++n) _Pragma("unroll") for (int k = 0; k < 2; ++k) dst[n][k] = *(const PG8_LAS bf16x8*)(lds + PG8_SB(b, h) + boff + n * 2048 + k * 1024); } while (0)
; #define PG8_MMA(ai, bj, At, Bt) do { __builtin_amdgcn_s_setprio(1); _Pragma("unroll") for (int m = 0; m < 4; ++m) _Pragma("unroll") for (int n = 0; n < 2; ++n) _Pragma("unroll") for (int k = 0; k < 2; ++k) \
;         acc[ai][bj][m][n] = __builtin_amdgcn_mfma_f32_16x16x32_bf16(Bt[n][k], At[m][k], acc[ai][bj][m][n], 0, 0, 0); __builtin_amdgcn_s_setprio(0); } while (0)
; #define PG8_WAIT_V(n) asm volatile("s_waitcnt vmcnt(" #n ")" ::: "memory")
; #define PG8_WAIT_L(n) asm volatile("s_waitcnt lgkmcnt(" #n ")" ::: "memory")
; #define PG8_BAR __builtin_amdgcn_s_barrier()
; #define PG8_SCHED __builtin_amdgcn_sched_barrier(0)
; template <class Epi, class Sched, bool ALIGN_EPI = false, bool SP2 = false>
; __device__ __forceinline__ void gemm_phase(PG8_LAS unsigned char* lds, const Gemm g, const Sched& S, const Epi& E) {
;     ...
;             const bool last = (t == nt - 2);
;             const char* a1 = cA + (size_t)(t + 1) * kstep;
;             const char* a2 = last ? nA : cA + (size_t)(t + 2) * kstep; const char* b2 = last ? nB : cB + (size_t)(t + 2) * kstep;
;             const char* a3 = a2 + kstep; const char* b3 = b2 + kstep;
;             if (last && has_next) S.a_ready(nxt);
;             if constexpr (SP2) {
;             PG8_LDB(B0, 0, 0); PG8_LDB(B1, 0, 1); PG8_SCHED; PG8_LDA(At, 0, 0); PG8_STAGE(PG8_SA(1, 1), a1 + hstep, voffA);
;             PG8_WAIT_V(8); PG8_WAIT_L(0); PG8_BAR; PG8_MMA(0, 0, At, B0); PG8_MMA(0, 1, At, B1); PG8_BAR; PG8_SCHED;
;             PG8_LDA(At, 0, 1); PG8_STAGE(PG8_SB(0, 0), b2, voffB); PG8_STAGE(PG8_SB(0, 1), b2 + hstep, voffB); PG8_STAGE(PG8_SA(0, 0), a2, voffA);
.LBB0_334:
	s_add_u32 s8, s6, 0xfffc0080
	s_addc_u32 s9, s7, -1
	s_add_i32 s18, 0, 0x10000
	s_cmp_eq_u32 s63, 12
	s_cselect_b32 s53, s5, s9
	s_cselect_b32 s52, s16, s8
	s_cselect_b32 s9, s38, s62
	s_cselect_b32 s8, s45, s47
	s_add_i32 s19, 0, 0x14000
	v_add_u32_e32 v158, s18, v155
	v_add_u32_e32 v174, s19, v155
	ds_read_b128 v[142:145], v158
	ds_read_b128 v[146:149], v158 offset:1024
	ds_read_b128 v[150:153], v158 offset:2048
	ds_read_b128 v[158:161], v158 offset:3072
	ds_read_b128 v[162:165], v174
	ds_read_b128 v[166:169], v174 offset:1024
	ds_read_b128 v[170:173], v174 offset:2048
	ds_read_b128 v[174:177], v174 offset:3072
	v_lshl_add_u64 v[206:207], s[6:7], 0, v[138:139]
	s_add_i32 m0, s11, 0xc000
	ds_read_b128 v[178:181], v157
	ds_read_b128 v[182:185], v157 offset:1024
	ds_read_b128 v[186:189], v157 offset:2048
	ds_read_b128 v[190:193], v157 offset:3072
	ds_read_b128 v[194:197], v157 offset:4096
	ds_read_b128 v[198:201], v157 offset:5120
	ds_read_b128 v[202:205], v157 offset:6144
	ds_read_b128 v[218:221], v157 offset:7168
	global_load_lds_dwordx4 v[206:207], off
	v_lshl_add_u64 v[206:207], s[6:7], 0, v[140:141]
	s_add_i32 m0, s11, 0xe000
	s_nop 0
	global_load_lds_dwordx4 v[206:207], off
	s_waitcnt vmcnt(8)
	s_waitcnt lgkmcnt(0)
	s_setprio 1
	s_barrier
	v_mfma_f32_16x16x32_bf16 v[124:127], v[142:145], v[178:181], v[124:127]
	v_mfma_f32_16x16x32_bf16 v[120:123], v[150:153], v[178:181], v[120:123]
	v_mfma_f32_16x16x32_bf16 v[108:111], v[142:145], v[186:189], v[108:111]
	v_mfma_f32_16x16x32_bf16 v[104:107], v[150:153], v[186:189], v[104:107]
	v_mfma_f32_16x16x32_bf16 v[92:95], v[142:145], v[194:197], v[92:95]
	v_mfma_f32_16x16x32_bf16 v[88:91], v[150:153], v[194:197], v[88:91]
	v_mfma_f32_16x16x32_bf16 v[76:79], v[142:145], v[202:205], v[76:79]
	v_mfma_f32_16x16x32_bf16 v[72:75], v[150:153], v[202:205], v[72:75]
	v_mfma_f32_16x16x32_bf16 v[124:127], v[146:149], v[182:185], v[124:127]
	v_mfma_f32_16x16x32_bf16 v[120:123], v[158:161], v[182:185], v[120:123]
	v_mfma_f32_16x16x32_bf16 v[108:111], v[146:149], v[190:193], v[108:111]
	v_mfma_f32_16x16x32_bf16 v[104:107], v[158:161], v[190:193], v[104:107]
	v_mfma_f32_16x16x32_bf16 v[92:95], v[146:149], v[198:201], v[92:95]
	v_mfma_f32_16x16x32_bf16 v[88:91], v[158:161], v[198:201], v[88:91]
	v_mfma_f32_16x16x32_bf16 v[76:79], v[146:149], v[218:221], v[76:79]
	v_mfma_f32_16x16x32_bf16 v[72:75], v[158:161], v[218:221], v[72:75]
	v_mfma_f32_16x16x32_bf16 v[116:119], v[162:165], v[178:181], v[116:119]
	v_mfma_f32_16x16x32_bf16 v[112:115], v[170:173], v[178:181], v[112:115]
	v_mfma_f32_16x16x32_bf16 v[100:103], v[162:165], v[186:189], v[100:103]
	v_mfma_f32_16x16x32_bf16 v[96:99], v[170:173], v[186:189], v[96:99]
	v_mfma_f32_16x16x32_bf16 v[84:87], v[162:165], v[194:197], v[84:87]
	v_mfma_f32_16x16x32_bf16 v[80:83], v[170:173], v[194:197], v[80:83]
	v_mfma_f32_16x16x32_bf16 v[68:71], v[162:165], v[202:205], v[68:71]
	v_mfma_f32_16x16x32_bf16 v[64:67], v[170:173], v[202:205], v[64:67]
	v_mfma_f32_16x16x32_bf16 v[116:119], v[166:169], v[182:185], v[116:119]
	v_mfma_f32_16x16x32_bf16 v[112:115], v[174:177], v[182:185], v[112:115]
	v_mfma_f32_16x16x32_bf16 v[100:103], v[166:169], v[190:193], v[100:103]
	v_mfma_f32_16x16x32_bf16 v[96:99], v[174:177], v[190:193], v[96:99]
	v_mfma_f32_16x16x32_bf16 v[84:87], v[166:169], v[198:201], v[84:87]
	v_mfma_f32_16x16x32_bf16 v[80:83], v[174:177], v[198:201], v[80:83]
	v_mfma_f32_16x16x32_bf16 v[68:71], v[166:169], v[218:221], v[68:71]
	v_mfma_f32_16x16x32_bf16 v[64:67], v[174:177], v[218:221], v[64:67]
	s_barrier
	s_setprio 0
	s_add_i32 s18, s18, s31
	v_lshl_add_u64 v[206:207], s[8:9], 0, v[130:131]
	s_mov_b32 m0, s18
	ds_read_b128 v[178:181], v157 offset:16384
	ds_read_b128 v[182:185], v157 offset:17408
	ds_read_b128 v[186:189], v157 offset:18432
	ds_read_b128 v[190:193], v157 offset:19456
	ds_read_b128 v[194:197], v157 offset:20480
	ds_read_b128 v[198:201], v157 offset:21504
	ds_read_b128 v[202:205], v157 offset:22528
	ds_read_b128 v[218:221], v157 offset:23552
	global_load_lds_dwordx4 v[206:207], off
	s_add_i32 m0, s18, 0x2000
	s_add_u32 s64, s8, 0x40000
	v_lshl_add_u64 v[212:213], s[8:9], 0, v[134:135]
	s_addc_u32 s65, s9, 0
	s_add_i32 s18, s19, s31
	global_load_lds_dwordx4 v[212:213], off
	v_lshl_add_u64 v[214:215], s[64:65], 0, v[130:131]
	s_mov_b32 m0, s18
	v_lshl_add_u64 v[222:223], s[52:53], 0, v[132:133]
	global_load_lds_dwordx4 v[214:215], off
	v_lshl_add_u64 v[214:215], s[64:65], 0, v[134:135]
	s_add_i32 m0, s18, 0x2000
	s_nop 0
	global_load_lds_dwordx4 v[214:215], off
	v_lshl_add_u64 v[214:215], s[52:53], 0, v[128:129]
	s_mov_b32 m0, s11
	s_nop 0
	global_load_lds_dwordx4 v[214:215], off
	s_mov_b32 m0, s35
	s_nop 0
	global_load_lds_dwordx4 v[222:223], off
	s_waitcnt vmcnt(8)
	s_waitcnt lgkmcnt(0)
	s_setprio 1
	s_barrier
; #define PG8_STAGE(bufoff, gbase, voff) do { _Pragma("unroll") for (int _i = 0; _i < 2; ++_i) \
;         __builtin_amdgcn_global_load_lds((const unsigned*)((const char*)(gbase) + (voff)[_i]), (PG8_LAS unsigned*)(lds + (bufoff) + ldsw + _i * 8192), 16, 0, 0); } while (0)
; #define PG8_LDA(dst, b, h) do { _Pragma("unroll") for (int m = 0; m < 4; ++m) _Pragma("unroll") for (int k = 0; k < 2; ++k) dst[m][k] = *(const PG8_LAS bf16x8*)(lds + PG8_SA(b, h) + aoff + m * 2048 + k * 1024); } while (0)
; #define PG8_LDB(dst, b, h) do { _Pragma("unroll") for (int n = 0; n < 2; ++n) _Pragma("unroll") for (int k = 0; k < 2; ++k) dst[n][k] = *(const PG8_LAS bf16x8*)(lds + PG8_SB(b, h) + boff + n * 2048 + k * 1024); } while (0)
; #define PG8_MMA(ai, bj, At, Bt) do { __builtin_amdgcn_s_setprio(1); _Pragma("unroll") for (int m = 0; m < 4; ++m) _Pragma("unroll") for (int n = 0; n < 2; ++n) _Pragma("unroll") for (int k = 0; k < 2; ++k) \
;         acc[ai][bj][m][n] = __builtin_amdgcn_mfma_f32_16x16x32_bf16(Bt[n][k], At[m][k], acc[ai][bj][m][n], 0, 0, 0); __builtin_amdgcn_s_setprio(0); } while (0)
; #define PG8_WAIT_V(n) asm volatile("s_waitcnt vmcnt(" #n ")" ::: "memory")
; #define PG8_WAIT_L(n) asm volatile("s_waitcnt lgkmcnt(" #n ")" ::: "memory")
; #define PG8_BAR __builtin_amdgcn_s_barrier()
; #define PG8_SCHED __builtin_amdgcn_sched_barrier(0)
; template <class Epi, class Sched, bool ALIGN_EPI = false, bool SP2 = false>
; __device__ __forceinline__ void gemm_phase(PG8_LAS unsigned char* lds, const Gemm g, const Sched& S, const Epi& E) {
;     ...
;             PG8_WAIT_V(8); PG8_WAIT_L(0); PG8_BAR; PG8_MMA(1, 0, At, B0); PG8_MMA(1, 1, At, B1); PG8_BAR; PG8_SCHED;
;             PG8_LDB(B0, 1, 0); PG8_LDB(B1, 1, 1); PG8_SCHED; PG8_LDA(At, 1, 0); PG8_STAGE(PG8_SA(0, 1), a2 + hstep, voffA);
;             PG8_WAIT_V(8); PG8_WAIT_L(0); PG8_BAR; PG8_MMA(0, 0, At, B0); PG8_MMA(0, 1, At, B1); PG8_BAR; PG8_SCHED;
	v_mfma_f32_16x16x32_bf16 v[60:63], v[142:145], v[178:181], v[60:63]
	v_mfma_f32_16x16x32_bf16 v[56:59], v[150:153], v[178:181], v[56:59]
	v_mfma_f32_16x16x32_bf16 v[44:47], v[142:145], v[186:189], v[44:47]
	v_mfma_f32_16x16x32_bf16 v[40:43], v[150:153], v[186:189], v[40:43]
	v_mfma_f32_16x16x32_bf16 v[28:31], v[142:145], v[194:197], v[28:31]
	v_mfma_f32_16x16x32_bf16 v[24:27], v[150:153], v[194:197], v[24:27]
	v_mfma_f32_16x16x32_bf16 v[12:15], v[142:145], v[202:205], v[12:15]
	v_mfma_f32_16x16x32_bf16 v[8:11], v[150:153], v[202:205], v[8:11]
	v_mfma_f32_16x16x32_bf16 v[60:63], v[146:149], v[182:185], v[60:63]
	v_mfma_f32_16x16x32_bf16 v[56:59], v[158:161], v[182:185], v[56:59]
	v_mfma_f32_16x16x32_bf16 v[44:47], v[146:149], v[190:193], v[44:47]
	v_mfma_f32_16x16x32_bf16 v[40:43], v[158:161], v[190:193], v[40:43]
	v_mfma_f32_16x16x32_bf16 v[28:31], v[146:149], v[198:201], v[28:31]
	v_mfma_f32_16x16x32_bf16 v[24:27], v[158:161], v[198:201], v[24:27]
	v_mfma_f32_16x16x32_bf16 v[12:15], v[146:149], v[218:221], v[12:15]
	v_mfma_f32_16x16x32_bf16 v[8:11], v[158:161], v[218:221], v[8:11]
	v_mfma_f32_16x16x32_bf16 v[52:55], v[162:165], v[178:181], v[52:55]
	v_mfma_f32_16x16x32_bf16 v[48:51], v[170:173], v[178:181], v[48:51]
	v_mfma_f32_16x16x32_bf16 v[36:39], v[162:165], v[186:189], v[36:39]
	v_mfma_f32_16x16x32_bf16 v[32:35], v[170:173], v[186:189], v[32:35]
	v_mfma_f32_16x16x32_bf16 v[20:23], v[162:165], v[194:197], v[20:23]
	v_mfma_f32_16x16x32_bf16 v[16:19], v[170:173], v[194:197], v[16:19]
	v_mfma_f32_16x16x32_bf16 v[4:7], v[162:165], v[202:205], v[4:7]
	v_mfma_f32_16x16x32_bf16 v[0:3], v[170:173], v[202:205], v[0:3]
	v_mfma_f32_16x16x32_bf16 v[52:55], v[166:169], v[182:185], v[52:55]
	v_mfma_f32_16x16x32_bf16 v[48:51], v[174:177], v[182:185], v[48:51]
	v_mfma_f32_16x16x32_bf16 v[36:39], v[166:169], v[190:193], v[36:39]
	v_mfma_f32_16x16x32_bf16 v[32:35], v[174:177], v[190:193], v[32:35]
	v_mfma_f32_16x16x32_bf16 v[20:23], v[166:169], v[198:201], v[20:23]
	v_mfma_f32_16x16x32_bf16 v[16:19], v[174:177], v[198:201], v[16:19]
	v_mfma_f32_16x16x32_bf16 v[4:7], v[166:169], v[218:221], v[4:7]
	v_mfma_f32_16x16x32_bf16 v[0:3], v[174:177], v[218:221], v[0:3]
	s_barrier
	s_setprio 0
	s_add_i32 s18, 0, 0x18000
	s_add_i32 s19, 0, 0x1c000
	v_add_u32_e32 v158, s18, v155
	v_add_u32_e32 v174, s19, v155
	ds_read_b128 v[142:145], v158
	ds_read_b128 v[146:149], v158 offset:1024
	ds_read_b128 v[150:153], v158 offset:2048
	ds_read_b128 v[158:161], v158 offset:3072
	ds_read_b128 v[162:165], v174
	ds_read_b128 v[166:169], v174 offset:1024
	ds_read_b128 v[170:173], v174 offset:2048
	ds_read_b128 v[174:177], v174 offset:3072
	s_add_u32 s52, s52, 0x40000
	s_addc_u32 s53, s53, 0
	s_mov_b32 m0, s54
	v_lshl_add_u64 v[224:225], s[52:53], 0, v[128:129]
	ds_read_b128 v[178:181], v157 offset:32768
	ds_read_b128 v[182:185], v157 offset:33792
	ds_read_b128 v[186:189], v157 offset:34816
	ds_read_b128 v[190:193], v157 offset:35840
	ds_read_b128 v[194:197], v157 offset:36864
	ds_read_b128 v[198:201], v157 offset:37888
	ds_read_b128 v[202:205], v157 offset:38912
	ds_read_b128 v[218:221], v157 offset:39936
	global_load_lds_dwordx4 v[224:225], off
	v_lshl_add_u64 v[224:225], s[52:53], 0, v[132:133]
	s_mov_b32 m0, s55
	s_nop 0
	global_load_lds_dwordx4 v[224:225], off
	s_waitcnt vmcnt(8)
	s_waitcnt lgkmcnt(0)
	s_setprio 1
	s_barrier
	v_mfma_f32_16x16x32_bf16 v[124:127], v[142:145], v[178:181], v[124:127]
	v_mfma_f32_16x16x32_bf16 v[120:123], v[150:153], v[178:181], v[120:123]
	v_mfma_f32_16x16x32_bf16 v[108:111], v[142:145], v[186:189], v[108:111]
	v_mfma_f32_16x16x32_bf16 v[104:107], v[150:153], v[186:189], v[104:107]
	v_mfma_f32_16x16x32_bf16 v[92:95], v[142:145], v[194:197], v[92:95]
	v_mfma_f32_16x16x32_bf16 v[88:91], v[150:153], v[194:197], v[88:91]
	v_mfma_f32_16x16x32_bf16 v[76:79], v[142:145], v[202:205], v[76:79]
	v_mfma_f32_16x16x32_bf16 v[72:75], v[150:153], v[202:205], v[72:75]
	v_mfma_f32_16x16x32_bf16 v[124:127], v[146:149], v[182:185], v[124:127]
	v_mfma_f32_16x16x32_bf16 v[120:123], v[158:161], v[182:185], v[120:123]
	v_mfma_f32_16x16x32_bf16 v[108:111], v[146:149], v[190:193], v[108:111]
	v_mfma_f32_16x16x32_bf16 v[104:107], v[158:161], v[190:193], v[104:107]
	v_mfma_f32_16x16x32_bf16 v[92:95], v[146:149], v[198:201], v[92:95]
	v_mfma_f32_16x16x32_bf16 v[88:91], v[158:161], v[198:201], v[88:91]
	v_mfma_f32_16x16x32_bf16 v[76:79], v[146:149], v[218:221], v[76:79]
	v_mfma_f32_16x16x32_bf16 v[72:75], v[158:161], v[218:221], v[72:75]
	v_mfma_f32_16x16x32_bf16 v[116:119], v[162:165], v[178:181], v[116:119]
	v_mfma_f32_16x16x32_bf16 v[112:115], v[170:173], v[178:181], v[112:115]
	v_mfma_f32_16x16x32_bf16 v[100:103], v[162:165], v[186:189], v[100:103]
	v_mfma_f32_16x16x32_bf16 v[96:99], v[170:173], v[186:189], v[96:99]
	v_mfma_f32_16x16x32_bf16 v[84:87], v[162:165], v[194:197], v[84:87]
	v_mfma_f32_16x16x32_bf16 v[80:83], v[170:173], v[194:197], v[80:83]
	v_mfma_f32_16x16x32_bf16 v[68:71], v[162:165], v[202:205], v[68:71]
	v_mfma_f32_16x16x32_bf16 v[64:67], v[170:173], v[202:205], v[64:67]
	v_mfma_f32_16x16x32_bf16 v[116:119], v[166:169], v[182:185], v[116:119]
	v_mfma_f32_16x16x32_bf16 v[112:115], v[174:177], v[182:185], v[112:115]
	v_mfma_f32_16x16x32_bf16 v[100:103], v[166:169], v[190:193], v[100:103]
	v_mfma_f32_16x16x32_bf16 v[96:99], v[174:177], v[190:193], v[96:99]
	v_mfma_f32_16x16x32_bf16 v[84:87], v[166:169], v[198:201], v[84:87]
	v_mfma_f32_16x16x32_bf16 v[80:83], v[174:177], v[198:201], v[80:83]
	v_mfma_f32_16x16x32_bf16 v[68:71], v[166:169], v[218:221], v[68:71]
	v_mfma_f32_16x16x32_bf16 v[64:67], v[174:177], v[218:221], v[64:67]
	s_barrier
; #define PG8_STAGE(bufoff, gbase, voff) do { _Pragma("unroll") for (int _i = 0; _i < 2; ++_i) \
;         __builtin_amdgcn_global_load_lds((const unsigned*)((const char*)(gbase) + (voff)[_i]), (PG8_LAS unsigned*)(lds + (bufoff) + ldsw + _i * 8192), 16, 0, 0); } while (0)
; #define PG8_LDA(dst, b, h) do { _Pragma("unroll") for (int m = 0; m < 4; ++m) _Pragma("unroll") for (int k = 0; k < 2; ++k) dst[m][k] = *(const PG8_LAS bf16x8*)(lds + PG8_SA(b, h) + aoff + m * 2048 + k * 1024); } while (0)
; #define PG8_MMA(ai, bj, At, Bt) do { __builtin_amdgcn_s_setprio(1); _Pragma("unroll") for (int m = 0; m < 4; ++m) _Pragma("unroll") for (int n = 0; n < 2; ++n) _Pragma("unroll") for (int k = 0; k < 2; ++k) \
;         acc[ai][bj][m][n] = __builtin_amdgcn_mfma_f32_16x16x32_bf16(Bt[n][k], At[m][k], acc[ai][bj][m][n], 0, 0, 0); __builtin_amdgcn_s_setprio(0); } while (0)
; #define PG8_WAIT_V(n) asm volatile("s_waitcnt vmcnt(" #n ")" ::: "memory")
; #define PG8_WAIT_L(n) asm volatile("s_waitcnt lgkmcnt(" #n ")" ::: "memory")
; #define PG8_BAR __builtin_amdgcn_s_barrier()
; #define PG8_SCHED __builtin_amdgcn_sched_barrier(0)
; template <class Epi, class Sched, bool ALIGN_EPI = false, bool SP2 = false>
; __device__ __forceinline__ void gemm_phase(PG8_LAS unsigned char* lds, const Gemm g, const Sched& S, const Epi& E) {
;     ...
;             PG8_LDA(At, 1, 1); PG8_STAGE(PG8_SB(1, 0), b3, voffB); PG8_STAGE(PG8_SB(1, 1), b3 + hstep, voffB); PG8_STAGE(PG8_SA(1, 0), a3, voffA);
;             PG8_WAIT_V(8); PG8_WAIT_L(0); PG8_BAR; PG8_MMA(1, 0, At, B0); PG8_MMA(1, 1, At, B1); PG8_BAR; PG8_SCHED;
;     ...
;         if constexpr (ALIGN_EPI) { if (wr == 0) PG8_BAR; }
	s_setprio 0
	s_add_i32 s18, s18, s31
	v_lshl_add_u64 v[206:207], v[206:207], 0, s[24:25]
	s_mov_b32 m0, s18
	ds_read_b128 v[178:181], v157 offset:49152
	ds_read_b128 v[182:185], v157 offset:50176
	ds_read_b128 v[186:189], v157 offset:51200
	ds_read_b128 v[190:193], v157 offset:52224
	ds_read_b128 v[194:197], v157 offset:53248
	ds_read_b128 v[198:201], v157 offset:54272
	ds_read_b128 v[202:205], v157 offset:55296
	ds_read_b128 v[218:221], v157 offset:56320
	global_load_lds_dwordx4 v[206:207], off
	s_add_i32 m0, s18, 0x2000
	s_add_u32 s8, s8, 0x40080
	v_lshl_add_u64 v[206:207], v[212:213], 0, s[24:25]
	s_addc_u32 s9, s9, 0
	s_add_i32 s18, s19, s31
	global_load_lds_dwordx4 v[206:207], off
	v_lshl_add_u64 v[206:207], s[8:9], 0, v[130:131]
	s_mov_b32 m0, s18
	s_nop 0
	global_load_lds_dwordx4 v[206:207], off
	v_lshl_add_u64 v[206:207], s[8:9], 0, v[134:135]
	s_add_i32 m0, s18, 0x2000
	s_nop 0
	global_load_lds_dwordx4 v[206:207], off
	v_lshl_add_u64 v[206:207], v[214:215], 0, s[24:25]
	s_mov_b32 m0, s57
	s_nop 0
	global_load_lds_dwordx4 v[206:207], off
	v_lshl_add_u64 v[206:207], v[222:223], 0, s[24:25]
	s_mov_b32 m0, s58
	s_nop 0
	global_load_lds_dwordx4 v[206:207], off
	s_waitcnt vmcnt(8)
	s_waitcnt lgkmcnt(0)
	s_setprio 1
	s_barrier
	v_mfma_f32_16x16x32_bf16 v[60:63], v[142:145], v[178:181], v[60:63]
	v_mfma_f32_16x16x32_bf16 v[56:59], v[150:153], v[178:181], v[56:59]
	v_mfma_f32_16x16x32_bf16 v[44:47], v[142:145], v[186:189], v[44:47]
	v_mfma_f32_16x16x32_bf16 v[40:43], v[150:153], v[186:189], v[40:43]
	v_mfma_f32_16x16x32_bf16 v[28:31], v[142:145], v[194:197], v[28:31]
	v_mfma_f32_16x16x32_bf16 v[24:27], v[150:153], v[194:197], v[24:27]
	v_mfma_f32_16x16x32_bf16 v[12:15], v[142:145], v[202:205], v[12:15]
	v_mfma_f32_16x16x32_bf16 v[8:11], v[150:153], v[202:205], v[8:11]
	v_mfma_f32_16x16x32_bf16 v[60:63], v[146:149], v[182:185], v[60:63]
	v_mfma_f32_16x16x32_bf16 v[56:59], v[158:161], v[182:185], v[56:59]
	v_mfma_f32_16x16x32_bf16 v[44:47], v[146:149], v[190:193], v[44:47]
	v_mfma_f32_16x16x32_bf16 v[40:43], v[158:161], v[190:193], v[40:43]
	v_mfma_f32_16x16x32_bf16 v[28:31], v[146:149], v[198:201], v[28:31]
	v_mfma_f32_16x16x32_bf16 v[24:27], v[158:161], v[198:201], v[24:27]
	v_mfma_f32_16x16x32_bf16 v[12:15], v[146:149], v[218:221], v[12:15]
	v_mfma_f32_16x16x32_bf16 v[8:11], v[158:161], v[218:221], v[8:11]
	v_mfma_f32_16x16x32_bf16 v[52:55], v[162:165], v[178:181], v[52:55]
	v_mfma_f32_16x16x32_bf16 v[48:51], v[170:173], v[178:181], v[48:51]
	v_mfma_f32_16x16x32_bf16 v[36:39], v[162:165], v[186:189], v[36:39]
	v_mfma_f32_16x16x32_bf16 v[32:35], v[170:173], v[186:189], v[32:35]
	v_mfma_f32_16x16x32_bf16 v[20:23], v[162:165], v[194:197], v[20:23]
	v_mfma_f32_16x16x32_bf16 v[16:19], v[170:173], v[194:197], v[16:19]
	v_mfma_f32_16x16x32_bf16 v[4:7], v[162:165], v[202:205], v[4:7]
	v_mfma_f32_16x16x32_bf16 v[0:3], v[170:173], v[202:205], v[0:3]
	v_mfma_f32_16x16x32_bf16 v[52:55], v[166:169], v[182:185], v[52:55]
	v_mfma_f32_16x16x32_bf16 v[48:51], v[174:177], v[182:185], v[48:51]
	v_mfma_f32_16x16x32_bf16 v[36:39], v[166:169], v[190:193], v[36:39]
	v_mfma_f32_16x16x32_bf16 v[32:35], v[174:177], v[190:193], v[32:35]
	v_mfma_f32_16x16x32_bf16 v[20:23], v[166:169], v[198:201], v[20:23]
	v_mfma_f32_16x16x32_bf16 v[16:19], v[174:177], v[198:201], v[16:19]
	v_mfma_f32_16x16x32_bf16 v[4:7], v[166:169], v[218:221], v[4:7]
	v_mfma_f32_16x16x32_bf16 v[0:3], v[174:177], v[218:221], v[0:3]
	s_barrier
	s_setprio 0
	s_add_i32 s63, s63, 2
	s_add_u32 s6, s6, 0x100
	s_addc_u32 s7, s7, 0
	s_add_u32 s47, s47, 0x100
	s_addc_u32 s62, s62, 0
	s_cmp_gt_u32 s63, 13
	s_cbranch_scc0 .LBB0_334
	s_and_b64 vcc, exec, s[26:27]
	s_cbranch_vccz .LBB0_337
	s_barrier
